# M4B gate loads issued up front (counted vmcnt); M1 rope64 epilogue table loads batched 16 ahead
# speedup vs baseline: 1.0740x; 1.0171x over previous
; #define MFMA(a, b, c) __builtin_amdgcn_mfma_f32_32x32x16_bf16((a), (b), (c), 0, 0, 0)
; template <int NB, int NS>
; DI void gemm_core(f32x16 (&acc)[NB][2][NS], const u16* __restrict__ A, long lda, long akcs,
;                   const u16* __restrict__ B0, const u16* __restrict__ B1, long ldb, int K, char* smem) {
;     ...
;   for (int kt = 0; kt < nk; ++kt) {
;     const int s = kt & 1;
;     if (kt + 1 < nk) GEMM_SSTORE(s ^ 1)
;     if (kt + 2 < nk) GEMM_GLOAD(kt + 2)
;     __builtin_amdgcn_sched_barrier(0);
;     const char* base = smem + s * STAGE;
; #pragma unroll
;     for (int kk = 0; kk < 4; ++kk) {
;       bf16x8 af[2], bfr[NB][NS];
; #pragma unroll
;       for (int ms = 0; ms < 2; ++ms) {
;         const int row = wm * 64 + ms * 32 + lr, ch = kk * 2 + lh;
;         af[ms] = *(const bf16x8*)(base + row * 128 + ((ch ^ ((row >> 1) & 7)) << 4));
;       }
; #pragma unroll
;       for (int b = 0; b < NB; ++b)
; #pragma unroll
;         for (int ns = 0; ns < NS; ++ns) {
;           const int row = wn * (32 * NS) + ns * 32 + lr, ch = kk * 2 + lh;
;           bfr[b][ns] = *(const bf16x8*)(base + A_BYTES + b * B_BYTES + row * 128 + ((ch ^ ((row >> 1) & 7)) << 4));
;         }
; #pragma unroll
;       for (int b = 0; b < NB; ++b)
; #pragma unroll
;         for (int ms = 0; ms < 2; ++ms)
; #pragma unroll
;           for (int ns = 0; ns < NS; ++ns) acc[b][ms][ns] = MFMA(af[ms], bfr[b][ns], acc[b][ms][ns]);
;     }
;     __syncthreads();
;   }
.LBB0_135:
	s_and_b32 s35, s6, 1
	s_xor_b32 s42, s35, 1
	s_mul_i32 s42, s42, 0xc000
	v_add_u32_e32 v0, s42, v165
	s_waitcnt vmcnt(4)
	ds_write_b128 v0, v[66:69]
	s_waitcnt vmcnt(0)
	ds_write_b128 v0, v[78:81] offset:8192
	ds_write_b128 v0, v[74:77] offset:16384
	ds_write_b128 v0, v[70:73] offset:24576
	ds_write_b128 v0, v[82:85] offset:32768
	ds_write_b128 v0, v[86:89] offset:40960
	v_lshl_add_u64 v[70:71], v[92:93], 0, s[10:11]
	s_mov_b32 s42, 0x14b14000
	v_add_co_u32_e32 v66, vcc, s42, v70
	s_mov_b32 s42, 0x14b54000
	s_nop 0
	v_addc_co_u32_e32 v67, vcc, 0, v71, vcc
	v_add_co_u32_e32 v72, vcc, s42, v70
	s_mov_b32 s42, 0x14b94000
	s_nop 0
	v_addc_co_u32_e32 v73, vcc, 0, v71, vcc
	global_load_dwordx4 v[78:81], v[72:73], off offset:3328
	v_add_co_u32_e32 v72, vcc, s42, v70
	s_mov_b32 s42, 0x14bd4000
	s_nop 0
	v_addc_co_u32_e32 v73, vcc, 0, v71, vcc
	v_add_co_u32_e32 v70, vcc, s42, v70
	v_lshl_add_u64 v[86:87], v[90:91], 0, s[10:11]
	s_nop 0
	v_addc_co_u32_e32 v71, vcc, 0, v71, vcc
	s_mov_b32 s42, 0x3180000
	v_add_co_u32_e32 v82, vcc, s42, v86
	s_mov_b32 s42, 0x3190000
	s_nop 0
	v_addc_co_u32_e32 v83, vcc, 0, v87, vcc
	v_add_co_u32_e32 v86, vcc, s42, v86
	global_load_dwordx4 v[66:69], v[66:67], off offset:3328
	s_nop 0
	v_addc_co_u32_e32 v87, vcc, 0, v87, vcc
	global_load_dwordx4 v[74:77], v[72:73], off offset:3328
	s_add_i32 s6, s6, 1
	global_load_dwordx4 v[70:73], v[70:71], off offset:3328
	s_nop 0
	global_load_dwordx4 v[82:85], v[82:83], off offset:256
	s_nop 0
	global_load_dwordx4 v[86:89], v[86:87], off offset:256
	s_mul_i32 s35, s35, 0xc000
	s_add_i32 s35, s35, 0
	v_add_u32_e32 v0, s35, v163
	v_add_u32_e32 v178, v0, v164
	ds_read_b128 v[166:169], v178
	v_add_u32_e32 v0, v0, v159
	ds_read_b128 v[170:173], v0 offset:32768
	ds_read_b128 v[174:177], v0 offset:36864
	v_add_u32_e32 v0, s35, v162
	s_add_u32 s10, s10, 0x80
	s_addc_u32 s11, s11, 0
	s_cmpk_lg_i32 s10, 0x300
	s_waitcnt lgkmcnt(1)
	v_mfma_f32_32x32x16_bf16 v[50:65], v[166:169], v[170:173], v[50:65]
	s_waitcnt lgkmcnt(0)
	v_mfma_f32_32x32x16_bf16 v[34:49], v[166:169], v[174:177], v[34:49]
	ds_read_b128 v[166:169], v178 offset:4096
	v_add_u32_e32 v178, v0, v164
	v_add_u32_e32 v0, v0, v159
	s_waitcnt lgkmcnt(0)
	v_mfma_f32_32x32x16_bf16 v[18:33], v[166:169], v[170:173], v[18:33]
	ds_read_b128 v[170:173], v0 offset:32768
	v_mfma_f32_32x32x16_bf16 v[2:17], v[166:169], v[174:177], v[2:17]
	ds_read_b128 v[166:169], v178
	ds_read_b128 v[174:177], v0 offset:36864
	v_add_u32_e32 v0, s35, v161
	s_waitcnt lgkmcnt(1)
	v_mfma_f32_32x32x16_bf16 v[50:65], v[166:169], v[170:173], v[50:65]
	s_waitcnt lgkmcnt(0)
	v_mfma_f32_32x32x16_bf16 v[34:49], v[166:169], v[174:177], v[34:49]
	ds_read_b128 v[166:169], v178 offset:4096
	v_add_u32_e32 v178, v0, v164
	v_add_u32_e32 v0, v0, v159
	s_waitcnt lgkmcnt(0)
	v_mfma_f32_32x32x16_bf16 v[18:33], v[166:169], v[170:173], v[18:33]
	ds_read_b128 v[170:173], v0 offset:32768
	v_mfma_f32_32x32x16_bf16 v[2:17], v[166:169], v[174:177], v[2:17]
	ds_read_b128 v[166:169], v178
	ds_read_b128 v[174:177], v0 offset:36864
	v_add_u32_e32 v0, s35, v160
	s_waitcnt lgkmcnt(1)
	v_mfma_f32_32x32x16_bf16 v[50:65], v[166:169], v[170:173], v[50:65]
	s_waitcnt lgkmcnt(0)
	v_mfma_f32_32x32x16_bf16 v[34:49], v[166:169], v[174:177], v[34:49]
	ds_read_b128 v[166:169], v178 offset:4096
	v_add_u32_e32 v178, v0, v164
	v_add_u32_e32 v0, v0, v159
	s_waitcnt lgkmcnt(0)
	v_mfma_f32_32x32x16_bf16 v[18:33], v[166:169], v[170:173], v[18:33]
	ds_read_b128 v[170:173], v0 offset:32768
	v_mfma_f32_32x32x16_bf16 v[2:17], v[166:169], v[174:177], v[2:17]
	ds_read_b128 v[166:169], v178
	ds_read_b128 v[174:177], v0 offset:36864
	s_waitcnt lgkmcnt(1)
	v_mfma_f32_32x32x16_bf16 v[50:65], v[166:169], v[170:173], v[50:65]
	s_waitcnt lgkmcnt(0)
	v_mfma_f32_32x32x16_bf16 v[34:49], v[166:169], v[174:177], v[34:49]
	ds_read_b128 v[166:169], v178 offset:4096
	s_waitcnt lgkmcnt(0)
	s_barrier
	v_mfma_f32_32x32x16_bf16 v[18:33], v[166:169], v[170:173], v[18:33]
	v_mfma_f32_32x32x16_bf16 v[2:17], v[166:169], v[174:177], v[2:17]
	s_cbranch_scc1 .LBB0_135
	v_add_u32_e32 v0, 0x10000, v165
	s_waitcnt vmcnt(4)
	ds_write_b128 v165, v[66:69] offset:49152
	ds_write_b128 v165, v[78:81] offset:57344
	s_waitcnt vmcnt(3)
	ds_write_b128 v0, v[74:77]
	v_add_u32_e32 v0, 0x12000, v165
	s_waitcnt vmcnt(2)
	ds_write_b128 v0, v[70:73]
	v_add_u32_e32 v0, 0x14000, v165
	s_waitcnt vmcnt(1)
	ds_write_b128 v0, v[82:85]
	v_add_u32_e32 v0, 0x16000, v165
	s_waitcnt vmcnt(0)
	ds_write_b128 v0, v[86:89]
	v_add_u32_e32 v0, 0, v163
	v_add_u32_e32 v78, v0, v164
	ds_read_b128 v[66:69], v78
	v_add_u32_e32 v0, v0, v159
	ds_read_b128 v[70:73], v0 offset:32768
	ds_read_b128 v[74:77], v0 offset:36864
	v_add_u32_e32 v0, 0, v162
	v_add_u32_e32 v82, v0, v164
	v_add_u32_e32 v0, v0, v159
	s_waitcnt lgkmcnt(1)
	v_mfma_f32_32x32x16_bf16 v[50:65], v[66:69], v[70:73], v[50:65]
	s_waitcnt lgkmcnt(0)
	v_mfma_f32_32x32x16_bf16 v[34:49], v[66:69], v[74:77], v[34:49]
	ds_read_b128 v[66:69], v78 offset:4096
	s_waitcnt lgkmcnt(0)
	v_mfma_f32_32x32x16_bf16 v[18:33], v[66:69], v[70:73], v[18:33]
	ds_read_b128 v[70:73], v0 offset:32768
	v_mfma_f32_32x32x16_bf16 v[2:17], v[66:69], v[74:77], v[2:17]
	ds_read_b128 v[66:69], v82
	ds_read_b128 v[74:77], v0 offset:36864
	v_add_u32_e32 v0, 0, v161
	v_add_u32_e32 v83, v0, v164
	v_add_u32_e32 v0, v0, v159
	s_waitcnt lgkmcnt(1)
	v_mfma_f32_32x32x16_bf16 v[50:65], v[66:69], v[70:73], v[50:65]
	s_waitcnt lgkmcnt(0)
	v_mfma_f32_32x32x16_bf16 v[34:49], v[66:69], v[74:77], v[34:49]
	ds_read_b128 v[66:69], v82 offset:4096
	s_waitcnt lgkmcnt(0)
	v_mfma_f32_32x32x16_bf16 v[18:33], v[66:69], v[70:73], v[18:33]
	ds_read_b128 v[70:73], v0 offset:32768
	v_mfma_f32_32x32x16_bf16 v[2:17], v[66:69], v[74:77], v[2:17]
	ds_read_b128 v[66:69], v83
	ds_read_b128 v[74:77], v0 offset:36864
	v_add_u32_e32 v0, 0, v160
	v_add_u32_e32 v84, v0, v164
	v_add_u32_e32 v0, v0, v159
	s_waitcnt lgkmcnt(1)
	v_mfma_f32_32x32x16_bf16 v[50:65], v[66:69], v[70:73], v[50:65]
	s_waitcnt lgkmcnt(0)
	v_mfma_f32_32x32x16_bf16 v[34:49], v[66:69], v[74:77], v[34:49]
	ds_read_b128 v[66:69], v83 offset:4096
	s_waitcnt lgkmcnt(0)
	v_mfma_f32_32x32x16_bf16 v[18:33], v[66:69], v[70:73], v[18:33]
	ds_read_b128 v[70:73], v0 offset:32768
	v_mfma_f32_32x32x16_bf16 v[2:17], v[66:69], v[74:77], v[2:17]
	ds_read_b128 v[66:69], v84
	ds_read_b128 v[74:77], v0 offset:36864
	s_waitcnt lgkmcnt(1)
	v_mfma_f32_32x32x16_bf16 v[50:65], v[66:69], v[70:73], v[50:65]
	s_waitcnt lgkmcnt(0)
	v_mfma_f32_32x32x16_bf16 v[34:49], v[66:69], v[74:77], v[34:49]
	ds_read_b128 v[66:69], v84 offset:4096
	s_waitcnt lgkmcnt(0)
	s_barrier
; #define MFMA(a, b, c) __builtin_amdgcn_mfma_f32_32x32x16_bf16((a), (b), (c), 0, 0, 0)
; DI size_t gate_off(size_t row4, int col) { return (((row4 >> 2) * 128 + (size_t)(col >> 5)) * 32 + (size_t)(col & 31)) * 4; }
; template <int NB, int NS>
; DI void gemm_core(f32x16 (&acc)[NB][2][NS], const u16* __restrict__ A, long lda, long akcs,
;                   const u16* __restrict__ B0, const u16* __restrict__ B1, long ldb, int K, char* smem) {
;     ...
;       for (int b = 0; b < NB; ++b)
; #pragma unroll
;         for (int ms = 0; ms < 2; ++ms)
; #pragma unroll
;           for (int ns = 0; ns < NS; ++ns) acc[b][ms][ns] = MFMA(af[ms], bfr[b][ns], acc[b][ms][ns]);
;     }
;     __syncthreads();
; DI void phase_m4b(const Params& p, int l, char* smem) {
;     ...
;       for (int ms = 0; ms < 2; ++ms)
; #pragma unroll
;         for (int ns = 0; ns < 2; ++ns)
; #pragma unroll
;           for (int gq = 0; gq < 4; ++gq) {
;             const size_t row = (size_t)mt * 256 + wm * 64 + ms * 32 + 8 * gq + 4 * lh;
;             const int col = nt * 128 + wn * 64 + ns * 32 + lr;
;             const unsigned long long gq64 = __builtin_nontemporal_load((const unsigned long long*)(gt + gate_off(row, br * 1024 + col)));
;             uint2 gv; gv.x = (unsigned)gq64; gv.y = (unsigned)(gq64 >> 32);
;             accm[ms][ns][4 * gq] += __uint_as_float(gv.x << 16) * ay[0][ms][ns][4 * gq];
;             accm[ms][ns][4 * gq + 1] += __uint_as_float(gv.x & 0xffff0000u) * ay[0][ms][ns][4 * gq + 1];
;             accm[ms][ns][4 * gq + 2] += __uint_as_float(gv.y << 16) * ay[0][ms][ns][4 * gq + 2];
;             accm[ms][ns][4 * gq + 3] += __uint_as_float(gv.y & 0xffff0000u) * ay[0][ms][ns][4 * gq + 3];
;           }
	v_mfma_f32_32x32x16_bf16 v[18:33], v[66:69], v[70:73], v[18:33]
	v_mfma_f32_32x32x16_bf16 v[2:17], v[66:69], v[74:77], v[2:17]
	s_add_i32 s6, 0, 0x14000
	v_add3_u32 v0, s6, v163, v159
	ds_read_b128 v[66:69], v78 offset:49152
	ds_read_b128 v[70:73], v78 offset:53248
	ds_read_b128 v[74:77], v0
	ds_read_b128 v[78:81], v0 offset:4096
	v_add3_u32 v0, s6, v162, v159
	s_add_i32 s7, s7, s36
	s_waitcnt lgkmcnt(1)
	v_mfma_f32_32x32x16_bf16 v[50:65], v[66:69], v[74:77], v[50:65]
	s_add_i32 s41, s41, 1
	s_add_u32 s4, s4, 0x100000
	s_addc_u32 s5, s5, 0
	s_add_u32 s8, s8, 0x400
	s_addc_u32 s9, s9, 0
	s_cmp_eq_u32 s41, 4
	s_waitcnt lgkmcnt(0)
	v_mfma_f32_32x32x16_bf16 v[34:49], v[66:69], v[78:81], v[34:49]
	v_mfma_f32_32x32x16_bf16 v[18:33], v[70:73], v[74:77], v[18:33]
	v_mfma_f32_32x32x16_bf16 v[2:17], v[70:73], v[78:81], v[2:17]
	ds_read_b128 v[66:69], v82 offset:49152
	ds_read_b128 v[70:73], v82 offset:53248
	ds_read_b128 v[74:77], v0
	ds_read_b128 v[78:81], v0 offset:4096
	v_add3_u32 v0, s6, v161, v159
	s_waitcnt lgkmcnt(1)
	v_mfma_f32_32x32x16_bf16 v[50:65], v[66:69], v[74:77], v[50:65]
	s_waitcnt lgkmcnt(0)
	v_mfma_f32_32x32x16_bf16 v[34:49], v[66:69], v[78:81], v[34:49]
	v_mfma_f32_32x32x16_bf16 v[18:33], v[70:73], v[74:77], v[18:33]
	v_mfma_f32_32x32x16_bf16 v[2:17], v[70:73], v[78:81], v[2:17]
	ds_read_b128 v[66:69], v83 offset:49152
	ds_read_b128 v[70:73], v83 offset:53248
	ds_read_b128 v[74:77], v0
	ds_read_b128 v[78:81], v0 offset:4096
	v_add3_u32 v0, s6, v160, v159
	s_waitcnt lgkmcnt(1)
	v_mfma_f32_32x32x16_bf16 v[50:65], v[66:69], v[74:77], v[50:65]
	s_waitcnt lgkmcnt(0)
	v_mfma_f32_32x32x16_bf16 v[34:49], v[66:69], v[78:81], v[34:49]
	v_mfma_f32_32x32x16_bf16 v[18:33], v[70:73], v[74:77], v[18:33]
	v_mfma_f32_32x32x16_bf16 v[2:17], v[70:73], v[78:81], v[2:17]
	ds_read_b128 v[66:69], v84 offset:49152
	ds_read_b128 v[70:73], v84 offset:53248
	ds_read_b128 v[74:77], v0
	ds_read_b128 v[78:81], v0 offset:4096
	v_mov_b32_e32 v0, v196
	s_waitcnt lgkmcnt(0)
	s_barrier
	v_mfma_f32_32x32x16_bf16 v[50:65], v[66:69], v[74:77], v[50:65]
	v_mfma_f32_32x32x16_bf16 v[34:49], v[66:69], v[78:81], v[34:49]
	v_ashrrev_i32_e32 v66, 1, v0
	v_and_b32_e32 v66, 0xffffffc0, v66
	v_ashrrev_i32_e32 v67, 31, v66
	v_lshl_add_u64 v[68:69], v[66:67], 0, s[62:63]
	v_lshrrev_b32_e32 v66, 3, v0
	v_and_or_b32 v68, v66, 4, v68
	v_lshlrev_b64 v[68:69], 5, v[68:69]
	v_mfma_f32_32x32x16_bf16 v[18:33], v[70:73], v[74:77], v[18:33]
	v_and_b32_e32 v69, 0xffffff, v69
	v_and_b32_e32 v68, 0xfffff880, v68
	v_mfma_f32_32x32x16_bf16 v[2:17], v[70:73], v[78:81], v[2:17]
	v_and_or_b32 v70, v0, 64, s7
	v_lshlrev_b32_e32 v0, 3, v0
	v_and_b32_e32 v0, 0xf8, v0
	v_lshl_add_u64 v[66:67], s[0:1], 0, v[0:1]
	v_lshrrev_b32_e32 v0, 5, v70
	v_lshl_add_u64 v[70:71], v[68:69], 0, v[0:1]
	v_lshlrev_b64 v[70:71], 8, v[70:71]
	v_lshl_add_u64 v[70:71], v[66:67], 0, v[70:71]
	v_lshrrev_b32_e32 v248, 1, v196
	v_and_b32_e32 v248, 0xffffffc0, v248
	v_lshrrev_b32_e32 v249, 3, v196
	v_and_b32_e32 v249, 4, v249
	v_add3_u32 v248, v248, v249, s62
	v_lshlrev_b32_e32 v248, 13, v248
	v_and_b32_e32 v249, 64, v196
	v_or_b32_e32 v249, s7, v249
	v_lshrrev_b32_e32 v249, 5, v249
	v_lshl_add_u32 v248, v249, 8, v248
	v_and_b32_e32 v249, 31, v196
	v_lshl_add_u32 v248, v249, 3, v248
	global_load_dwordx2 v[216:217], v248, s[0:1] nt
	v_add_u32_e32 v249, 0x10000, v248
	global_load_dwordx2 v[218:219], v249, s[0:1] nt
	v_add_u32_e32 v249, 0x20000, v248
	global_load_dwordx2 v[220:221], v249, s[0:1] nt
	v_add_u32_e32 v249, 0x30000, v248
	global_load_dwordx2 v[222:223], v249, s[0:1] nt
	global_load_dwordx2 v[224:225], v248, s[0:1] offset:256 nt
	v_add_u32_e32 v249, 0x10000, v248
	global_load_dwordx2 v[226:227], v249, s[0:1] offset:256 nt
	v_add_u32_e32 v249, 0x20000, v248
	global_load_dwordx2 v[228:229], v249, s[0:1] offset:256 nt
	v_add_u32_e32 v249, 0x30000, v248
	global_load_dwordx2 v[230:231], v249, s[0:1] offset:256 nt
	v_add_u32_e32 v249, 0x40000, v248
	global_load_dwordx2 v[232:233], v249, s[0:1] nt
	v_add_u32_e32 v249, 0x50000, v248
	global_load_dwordx2 v[234:235], v249, s[0:1] nt
	v_add_u32_e32 v249, 0x60000, v248
	global_load_dwordx2 v[236:237], v249, s[0:1] nt
	v_add_u32_e32 v249, 0x70000, v248
	global_load_dwordx2 v[238:239], v249, s[0:1] nt
	v_add_u32_e32 v249, 0x40000, v248
	global_load_dwordx2 v[240:241], v249, s[0:1] offset:256 nt
	v_add_u32_e32 v249, 0x50000, v248
	global_load_dwordx2 v[242:243], v249, s[0:1] offset:256 nt
	v_add_u32_e32 v249, 0x60000, v248
	global_load_dwordx2 v[244:245], v249, s[0:1] offset:256 nt
	v_add_u32_e32 v249, 0x70000, v248
	global_load_dwordx2 v[246:247], v249, s[0:1] offset:256 nt
	s_waitcnt vmcnt(15)
	v_lshlrev_b32_e32 v72, 16, v216
	v_fmac_f32_e32 v158, v50, v72
	v_and_b32_e32 v50, 0xffff0000, v216
	v_fmac_f32_e32 v157, v51, v50
	v_lshlrev_b32_e32 v50, 16, v217
	v_fmac_f32_e32 v156, v52, v50
	v_and_b32_e32 v50, 0xffff0000, v217
	v_or_b32_e32 v70, 0x100, v68
	v_mov_b32_e32 v71, v69
	v_fmac_f32_e32 v155, v53, v50
	v_lshl_add_u64 v[50:51], v[70:71], 0, v[0:1]
	v_lshlrev_b64 v[50:51], 8, v[50:51]
	v_lshl_add_u64 v[50:51], v[66:67], 0, v[50:51]
	v_mov_b32_e32 v53, v69
	s_waitcnt vmcnt(14)
	v_lshlrev_b32_e32 v52, 16, v218
	v_and_b32_e32 v50, 0xffff0000, v218
	v_fmac_f32_e32 v152, v55, v50
	v_lshlrev_b32_e32 v50, 16, v219
	v_fmac_f32_e32 v153, v54, v52
	v_fmac_f32_e32 v151, v56, v50
	v_and_b32_e32 v50, 0xffff0000, v219
	v_or_b32_e32 v54, 0x200, v68
	v_mov_b32_e32 v55, v69
	v_fmac_f32_e32 v150, v57, v50
	v_lshl_add_u64 v[50:51], v[54:55], 0, v[0:1]
	v_lshlrev_b64 v[50:51], 8, v[50:51]
	v_lshl_add_u64 v[50:51], v[66:67], 0, v[50:51]
	s_waitcnt vmcnt(13)
; DI size_t gate_off(size_t row4, int col) { return (((row4 >> 2) * 128 + (size_t)(col >> 5)) * 32 + (size_t)(col & 31)) * 4; }
; DI void phase_m4b(const Params& p, int l, char* smem) {
;     ...
;       for (int ms = 0; ms < 2; ++ms)
; #pragma unroll
;         for (int ns = 0; ns < 2; ++ns)
; #pragma unroll
;           for (int gq = 0; gq < 4; ++gq) {
;             const size_t row = (size_t)mt * 256 + wm * 64 + ms * 32 + 8 * gq + 4 * lh;
;             const int col = nt * 128 + wn * 64 + ns * 32 + lr;
;             const unsigned long long gq64 = __builtin_nontemporal_load((const unsigned long long*)(gt + gate_off(row, br * 1024 + col)));
;             uint2 gv; gv.x = (unsigned)gq64; gv.y = (unsigned)(gq64 >> 32);
;             accm[ms][ns][4 * gq] += __uint_as_float(gv.x << 16) * ay[0][ms][ns][4 * gq];
;             accm[ms][ns][4 * gq + 1] += __uint_as_float(gv.x & 0xffff0000u) * ay[0][ms][ns][4 * gq + 1];
;             accm[ms][ns][4 * gq + 2] += __uint_as_float(gv.y << 16) * ay[0][ms][ns][4 * gq + 2];
;             accm[ms][ns][4 * gq + 3] += __uint_as_float(gv.y & 0xffff0000u) * ay[0][ms][ns][4 * gq + 3];
;           }
	v_lshlrev_b32_e32 v52, 16, v220
	v_and_b32_e32 v50, 0xffff0000, v220
	v_fmac_f32_e32 v148, v59, v50
	v_lshlrev_b32_e32 v50, 16, v221
	v_fmac_f32_e32 v149, v58, v52
	v_fmac_f32_e32 v147, v60, v50
	v_and_b32_e32 v50, 0xffff0000, v221
	v_or_b32_e32 v52, 0x300, v68
	v_fmac_f32_e32 v146, v61, v50
	v_lshl_add_u64 v[50:51], v[52:53], 0, v[0:1]
	v_lshlrev_b64 v[50:51], 8, v[50:51]
	v_lshl_add_u64 v[50:51], v[66:67], 0, v[50:51]
	s_waitcnt vmcnt(12)
	v_lshlrev_b32_e32 v56, 16, v222
	v_and_b32_e32 v50, 0xffff0000, v222
	v_fmac_f32_e32 v144, v63, v50
	v_lshlrev_b32_e32 v50, 16, v223
	v_fmac_f32_e32 v143, v64, v50
	v_and_b32_e32 v50, 0xffff0000, v223
	v_fmac_f32_e32 v142, v65, v50
	v_or_b32_e32 v50, 1, v0
	v_mov_b32_e32 v51, v1
	v_fmac_f32_e32 v145, v62, v56
	v_lshl_add_u64 v[56:57], v[68:69], 0, v[50:51]
	v_lshlrev_b64 v[56:57], 8, v[56:57]
	v_lshl_add_u64 v[56:57], v[66:67], 0, v[56:57]
	s_waitcnt vmcnt(11)
	v_lshlrev_b32_e32 v58, 16, v224
	v_fmac_f32_e32 v141, v34, v58
	v_and_b32_e32 v34, 0xffff0000, v224
	v_fmac_f32_e32 v140, v35, v34
	v_lshlrev_b32_e32 v34, 16, v225
	v_fmac_f32_e32 v139, v36, v34
	v_and_b32_e32 v34, 0xffff0000, v225
	v_fmac_f32_e32 v138, v37, v34
	v_lshl_add_u64 v[34:35], v[70:71], 0, v[50:51]
	v_lshlrev_b64 v[34:35], 8, v[34:35]
	v_lshl_add_u64 v[34:35], v[66:67], 0, v[34:35]
	s_waitcnt vmcnt(10)
	v_lshlrev_b32_e32 v36, 16, v226
	v_and_b32_e32 v34, 0xffff0000, v226
	v_fmac_f32_e32 v136, v39, v34
	v_lshlrev_b32_e32 v34, 16, v227
	v_fmac_f32_e32 v135, v40, v34
	v_and_b32_e32 v34, 0xffff0000, v227
	v_fmac_f32_e32 v134, v41, v34
	v_lshl_add_u64 v[34:35], v[54:55], 0, v[50:51]
	v_lshlrev_b64 v[34:35], 8, v[34:35]
	v_lshl_add_u64 v[34:35], v[66:67], 0, v[34:35]
	v_fmac_f32_e32 v137, v38, v36
	s_waitcnt vmcnt(9)
	v_lshlrev_b32_e32 v36, 16, v228
	v_and_b32_e32 v34, 0xffff0000, v228
	v_fmac_f32_e32 v132, v43, v34
	v_lshlrev_b32_e32 v34, 16, v229
	v_fmac_f32_e32 v131, v44, v34
	v_and_b32_e32 v34, 0xffff0000, v229
	v_fmac_f32_e32 v130, v45, v34
	v_lshl_add_u64 v[34:35], v[52:53], 0, v[50:51]
	v_lshlrev_b64 v[34:35], 8, v[34:35]
	v_lshl_add_u64 v[34:35], v[66:67], 0, v[34:35]
	v_fmac_f32_e32 v133, v42, v36
	s_waitcnt vmcnt(8)
	v_lshlrev_b32_e32 v36, 16, v230
	v_and_b32_e32 v34, 0xffff0000, v230
	v_fmac_f32_e32 v128, v47, v34
	v_lshlrev_b32_e32 v34, 16, v231
	v_fmac_f32_e32 v127, v48, v34
	v_and_b32_e32 v34, 0xffff0000, v231
	v_fmac_f32_e32 v126, v49, v34
	v_or_b32_e32 v34, 0x400, v68
	v_mov_b32_e32 v35, v69
	v_fmac_f32_e32 v129, v46, v36
	v_lshl_add_u64 v[36:37], v[34:35], 0, v[0:1]
	v_lshlrev_b64 v[36:37], 8, v[36:37]
	v_lshl_add_u64 v[36:37], v[66:67], 0, v[36:37]
	s_waitcnt vmcnt(7)
	v_lshlrev_b32_e32 v38, 16, v232
	v_fmac_f32_e32 v125, v18, v38
	v_and_b32_e32 v18, 0xffff0000, v232
	v_fmac_f32_e32 v124, v19, v18
	v_lshlrev_b32_e32 v18, 16, v233
	v_fmac_f32_e32 v123, v20, v18
	v_and_b32_e32 v18, 0xffff0000, v233
	v_fmac_f32_e32 v122, v21, v18
	v_or_b32_e32 v20, 0x500, v68
	v_mov_b32_e32 v21, v69
	v_lshl_add_u64 v[18:19], v[20:21], 0, v[0:1]
	v_lshlrev_b64 v[18:19], 8, v[18:19]
	v_lshl_add_u64 v[18:19], v[66:67], 0, v[18:19]
	s_waitcnt vmcnt(6)
	v_lshlrev_b32_e32 v36, 16, v234
	v_and_b32_e32 v18, 0xffff0000, v234
	v_fmac_f32_e32 v120, v23, v18
	v_lshlrev_b32_e32 v18, 16, v235
	v_fmac_f32_e32 v119, v24, v18
	v_and_b32_e32 v18, 0xffff0000, v235
	v_fmac_f32_e32 v118, v25, v18
	v_or_b32_e32 v18, 0x600, v68
	v_mov_b32_e32 v19, v69
	v_fmac_f32_e32 v121, v22, v36
	v_lshl_add_u64 v[22:23], v[18:19], 0, v[0:1]
	v_lshlrev_b64 v[22:23], 8, v[22:23]
	v_lshl_add_u64 v[22:23], v[66:67], 0, v[22:23]
	v_or_b32_e32 v68, 0x700, v68
	s_waitcnt vmcnt(5)
	v_lshlrev_b32_e32 v24, 16, v236
	v_and_b32_e32 v22, 0xffff0000, v236
	v_fmac_f32_e32 v116, v27, v22
	v_lshlrev_b32_e32 v22, 16, v237
	v_fmac_f32_e32 v115, v28, v22
	v_and_b32_e32 v22, 0xffff0000, v237
	v_fmac_f32_e32 v114, v29, v22
	v_lshl_add_u64 v[22:23], v[68:69], 0, v[0:1]
	v_lshlrev_b64 v[22:23], 8, v[22:23]
	v_lshl_add_u64 v[22:23], v[66:67], 0, v[22:23]
	v_fmac_f32_e32 v117, v26, v24
	s_waitcnt vmcnt(4)
	v_lshlrev_b32_e32 v0, 16, v238
	v_fmac_f32_e32 v113, v30, v0
	v_and_b32_e32 v0, 0xffff0000, v238
	v_fmac_f32_e32 v112, v31, v0
	v_lshlrev_b32_e32 v0, 16, v239
	v_fmac_f32_e32 v111, v32, v0
	v_and_b32_e32 v0, 0xffff0000, v239
	v_lshl_add_u64 v[22:23], v[34:35], 0, v[50:51]
	v_lshlrev_b64 v[22:23], 8, v[22:23]
	v_lshl_add_u64 v[22:23], v[66:67], 0, v[22:23]
	v_fmac_f32_e32 v110, v33, v0
	s_waitcnt vmcnt(3)
	v_lshlrev_b32_e32 v0, 16, v240
	v_fmac_f32_e32 v109, v2, v0
	v_and_b32_e32 v0, 0xffff0000, v240
	v_fmac_f32_e32 v108, v3, v0
	v_lshl_add_u64 v[2:3], v[20:21], 0, v[50:51]
	v_lshlrev_b64 v[2:3], 8, v[2:3]
	v_lshl_add_u64 v[2:3], v[66:67], 0, v[2:3]
	v_lshlrev_b32_e32 v0, 16, v241
	v_fmac_f32_e32 v107, v4, v0
	v_and_b32_e32 v0, 0xffff0000, v241
	v_fmac_f32_e32 v106, v5, v0
	s_waitcnt vmcnt(2)
	v_lshlrev_b32_e32 v0, 16, v242
	v_fmac_f32_e32 v105, v6, v0
	v_and_b32_e32 v0, 0xffff0000, v242
	v_fmac_f32_e32 v104, v7, v0
	v_lshlrev_b32_e32 v0, 16, v243
	v_fmac_f32_e32 v103, v8, v0
	v_and_b32_e32 v0, 0xffff0000, v243
	v_lshl_add_u64 v[2:3], v[18:19], 0, v[50:51]
	v_lshlrev_b64 v[2:3], 8, v[2:3]
	v_lshl_add_u64 v[2:3], v[66:67], 0, v[2:3]
	v_fmac_f32_e32 v102, v9, v0
	s_waitcnt vmcnt(1)
	v_lshlrev_b32_e32 v0, 16, v244
	v_fmac_f32_e32 v101, v10, v0
	v_and_b32_e32 v0, 0xffff0000, v244
	v_fmac_f32_e32 v100, v11, v0
	v_lshlrev_b32_e32 v0, 16, v245
	v_fmac_f32_e32 v99, v12, v0
	v_and_b32_e32 v0, 0xffff0000, v245
	v_lshl_add_u64 v[2:3], v[68:69], 0, v[50:51]
	v_lshlrev_b64 v[2:3], 8, v[2:3]
	v_lshl_add_u64 v[2:3], v[66:67], 0, v[2:3]
	v_fmac_f32_e32 v98, v13, v0
	s_waitcnt vmcnt(0)
	v_lshlrev_b32_e32 v0, 16, v246
	v_fmac_f32_e32 v97, v14, v0
	v_and_b32_e32 v0, 0xffff0000, v246
	v_fmac_f32_e32 v96, v15, v0
	v_lshlrev_b32_e32 v0, 16, v247
	v_fmac_f32_e32 v95, v16, v0
	v_and_b32_e32 v0, 0xffff0000, v247
	v_fmac_f32_e32 v94, v17, v0
	s_cbranch_scc0 .LBB0_134
; DI u16 f2bf(float x) { return (u16)(pack2(x, 0.f) & 0xffffu); }
; DI int crow(int i, int h) { return (i & 3) + 8 * (i >> 2) + 4 * h; }
; DI void phase_m4b(const Params& p, int l, char* smem) {
;     ...
;     EPI_IDS
; #pragma unroll
;     for (int ms = 0; ms < 2; ++ms)
; #pragma unroll
;       for (int ns = 0; ns < 2; ++ns)
; #pragma unroll
;         for (int i = 0; i < 16; ++i) {
;           const size_t row = (size_t)mt * 256 + wm * 64 + ms * 32 + crow(i, lh);
;           mg[row * D + nt * 128 + wn * 64 + ns * 32 + lr] = f2bf(accm[ms][ns][i]);
;         }
	v_mov_b32_e32 v0, v196
	s_lshl_b32 s4, s36, 1
	v_ashrrev_i32_e32 v2, 1, v0
	v_and_b32_e32 v2, 0xffffffc0, v2
	v_and_b32_e32 v4, 64, v0
	v_and_b32_e32 v6, 31, v0
	v_ashrrev_i32_e32 v3, 31, v2
	v_lshrrev_b32_e32 v0, 3, v0
	s_add_u32 s4, s18, s4
	v_lshl_add_u64 v[2:3], v[2:3], 0, s[62:63]
	v_and_b32_e32 v38, 4, v0
	s_addc_u32 s5, s19, 0
	v_lshlrev_b32_e32 v0, 1, v4
	v_lshl_add_u64 v[4:5], s[4:5], 0, v[0:1]
	v_lshlrev_b32_e32 v0, 1, v6
	v_or_b32_e32 v6, v2, v38
	v_mov_b32_e32 v7, v3
	v_lshl_add_u64 v[4:5], v[4:5], 0, v[0:1]
	v_lshlrev_b64 v[6:7], 11, v[6:7]
	v_cvt_pk_bf16_f32 v0, v158, s0
	v_lshl_add_u64 v[6:7], v[4:5], 0, v[6:7]
	global_store_short v[6:7], v0, off
	v_or_b32_e32 v0, 1, v38
	v_or_b32_e32 v8, v2, v0
	v_mov_b32_e32 v9, v3
	v_lshlrev_b64 v[8:9], 11, v[8:9]
	v_cvt_pk_bf16_f32 v10, v157, s0
	v_lshl_add_u64 v[8:9], v[4:5], 0, v[8:9]
	v_or_b32_e32 v39, 2, v38
	global_store_short v[8:9], v10, off
	v_or_b32_e32 v10, v2, v39
	v_mov_b32_e32 v11, v3
	v_lshlrev_b64 v[10:11], 11, v[10:11]
	v_cvt_pk_bf16_f32 v12, v156, s0
	v_lshl_add_u64 v[10:11], v[4:5], 0, v[10:11]
	v_or_b32_e32 v40, 3, v38
	global_store_short v[10:11], v12, off
	v_or_b32_e32 v12, v2, v40
	v_mov_b32_e32 v13, v3
	v_lshlrev_b64 v[12:13], 11, v[12:13]
	v_cvt_pk_bf16_f32 v14, v155, s0
	v_lshl_add_u64 v[12:13], v[4:5], 0, v[12:13]
	v_or_b32_e32 v41, 8, v38
	global_store_short v[12:13], v14, off
	v_or_b32_e32 v14, v2, v41
	v_mov_b32_e32 v15, v3
	v_lshlrev_b64 v[14:15], 11, v[14:15]
	v_cvt_pk_bf16_f32 v16, v153, s0
	v_lshl_add_u64 v[14:15], v[4:5], 0, v[14:15]
	v_or_b32_e32 v42, 9, v38
	global_store_short v[14:15], v16, off
	v_or_b32_e32 v16, v2, v42
	v_mov_b32_e32 v17, v3
	v_lshlrev_b64 v[16:17], 11, v[16:17]
	v_cvt_pk_bf16_f32 v18, v152, s0
	v_lshl_add_u64 v[16:17], v[4:5], 0, v[16:17]
	v_or_b32_e32 v43, 10, v38
	global_store_short v[16:17], v18, off
	v_or_b32_e32 v18, v2, v43
	v_mov_b32_e32 v19, v3
	v_lshlrev_b64 v[18:19], 11, v[18:19]
	v_cvt_pk_bf16_f32 v20, v151, s0
	v_lshl_add_u64 v[18:19], v[4:5], 0, v[18:19]
	v_or_b32_e32 v44, 11, v38
	global_store_short v[18:19], v20, off
	v_or_b32_e32 v20, v2, v44
	v_mov_b32_e32 v21, v3
	v_lshlrev_b64 v[20:21], 11, v[20:21]
	v_cvt_pk_bf16_f32 v22, v150, s0
	v_lshl_add_u64 v[20:21], v[4:5], 0, v[20:21]
	v_or_b32_e32 v45, 16, v38
	global_store_short v[20:21], v22, off
	v_or_b32_e32 v22, v2, v45
	v_mov_b32_e32 v23, v3
	v_lshlrev_b64 v[22:23], 11, v[22:23]
	v_cvt_pk_bf16_f32 v24, v149, s0
	v_lshl_add_u64 v[22:23], v[4:5], 0, v[22:23]
	v_or_b32_e32 v46, 17, v38
	global_store_short v[22:23], v24, off
	v_or_b32_e32 v24, v2, v46
	v_mov_b32_e32 v25, v3
	v_lshlrev_b64 v[24:25], 11, v[24:25]
	v_cvt_pk_bf16_f32 v26, v148, s0
	v_lshl_add_u64 v[24:25], v[4:5], 0, v[24:25]
	v_or_b32_e32 v47, 18, v38
	global_store_short v[24:25], v26, off
	v_or_b32_e32 v26, v2, v47
	v_mov_b32_e32 v27, v3
	v_lshlrev_b64 v[26:27], 11, v[26:27]
	v_cvt_pk_bf16_f32 v28, v147, s0
	v_lshl_add_u64 v[26:27], v[4:5], 0, v[26:27]
	v_or_b32_e32 v48, 19, v38
	global_store_short v[26:27], v28, off
	v_or_b32_e32 v28, v2, v48
	v_mov_b32_e32 v29, v3
	v_lshlrev_b64 v[28:29], 11, v[28:29]
	v_cvt_pk_bf16_f32 v30, v146, s0
	v_lshl_add_u64 v[28:29], v[4:5], 0, v[28:29]
	v_or_b32_e32 v49, 24, v38
	global_store_short v[28:29], v30, off
	v_or_b32_e32 v30, v2, v49
	v_mov_b32_e32 v31, v3
	v_lshlrev_b64 v[30:31], 11, v[30:31]
	v_cvt_pk_bf16_f32 v32, v145, s0
	v_lshl_add_u64 v[30:31], v[4:5], 0, v[30:31]
	v_or_b32_e32 v50, 25, v38
	global_store_short v[30:31], v32, off
	v_or_b32_e32 v32, v2, v50
	v_mov_b32_e32 v33, v3
	v_lshlrev_b64 v[32:33], 11, v[32:33]
	v_cvt_pk_bf16_f32 v34, v144, s0
	v_lshl_add_u64 v[32:33], v[4:5], 0, v[32:33]
	v_or_b32_e32 v51, 26, v38
	global_store_short v[32:33], v34, off
	v_or_b32_e32 v34, v2, v51
	v_mov_b32_e32 v35, v3
	v_lshlrev_b64 v[34:35], 11, v[34:35]
	v_cvt_pk_bf16_f32 v36, v143, s0
	v_lshl_add_u64 v[34:35], v[4:5], 0, v[34:35]
	v_or_b32_e32 v52, 27, v38
	global_store_short v[34:35], v36, off
	v_or_b32_e32 v36, v2, v52
	v_mov_b32_e32 v37, v3
	v_lshlrev_b64 v[36:37], 11, v[36:37]
	v_cvt_pk_bf16_f32 v53, v142, s0
	v_lshl_add_u64 v[36:37], v[4:5], 0, v[36:37]
	global_store_short v[36:37], v53, off
	v_cvt_pk_bf16_f32 v53, v141, s0
	global_store_short v[6:7], v53, off offset:64
	v_cvt_pk_bf16_f32 v6, v140, s0
	global_store_short v[8:9], v6, off offset:64
	v_cvt_pk_bf16_f32 v6, v139, s0
	global_store_short v[10:11], v6, off offset:64
	v_cvt_pk_bf16_f32 v6, v138, s0
	global_store_short v[12:13], v6, off offset:64
	v_cvt_pk_bf16_f32 v6, v137, s0
	global_store_short v[14:15], v6, off offset:64
	v_cvt_pk_bf16_f32 v6, v136, s0
	global_store_short v[16:17], v6, off offset:64
	v_cvt_pk_bf16_f32 v6, v135, s0
	global_store_short v[18:19], v6, off offset:64
	v_cvt_pk_bf16_f32 v6, v134, s0
	global_store_short v[20:21], v6, off offset:64
	v_cvt_pk_bf16_f32 v6, v133, s0
; DI u16 f2bf(float x) { return (u16)(pack2(x, 0.f) & 0xffffu); }
; DI int crow(int i, int h) { return (i & 3) + 8 * (i >> 2) + 4 * h; }
; DI void phase_m4b(const Params& p, int l, char* smem) {
;     ...
;   for (int qq = blockIdx.x >> 3; qq < 64; qq += (gridDim.x >> 3)) {
;     ...
;     EPI_IDS
; #pragma unroll
;     for (int ms = 0; ms < 2; ++ms)
; #pragma unroll
;       for (int ns = 0; ns < 2; ++ns)
; #pragma unroll
;         for (int i = 0; i < 16; ++i) {
;           const size_t row = (size_t)mt * 256 + wm * 64 + ms * 32 + crow(i, lh);
;           mg[row * D + nt * 128 + wn * 64 + ns * 32 + lr] = f2bf(accm[ms][ns][i]);
;         }
	global_store_short v[22:23], v6, off offset:64
	v_cvt_pk_bf16_f32 v6, v132, s0
	global_store_short v[24:25], v6, off offset:64
	v_cvt_pk_bf16_f32 v6, v131, s0
	global_store_short v[26:27], v6, off offset:64
	v_cvt_pk_bf16_f32 v6, v130, s0
	global_store_short v[28:29], v6, off offset:64
	v_cvt_pk_bf16_f32 v6, v129, s0
	global_store_short v[30:31], v6, off offset:64
	v_cvt_pk_bf16_f32 v6, v128, s0
	global_store_short v[32:33], v6, off offset:64
	v_cvt_pk_bf16_f32 v6, v127, s0
	global_store_short v[34:35], v6, off offset:64
	v_cvt_pk_bf16_f32 v6, v126, s0
	global_store_short v[36:37], v6, off offset:64
	v_or_b32_e32 v36, 32, v2
	v_or_b32_e32 v2, v36, v38
	v_lshlrev_b64 v[6:7], 11, v[2:3]
	v_cvt_pk_bf16_f32 v8, v125, s0
	v_lshl_add_u64 v[6:7], v[4:5], 0, v[6:7]
	v_or_b32_e32 v2, v36, v0
	global_store_short v[6:7], v8, off
	v_lshlrev_b64 v[8:9], 11, v[2:3]
	v_or_b32_e32 v2, v36, v39
	v_cvt_pk_bf16_f32 v0, v124, s0
	v_lshl_add_u64 v[8:9], v[4:5], 0, v[8:9]
	v_lshlrev_b64 v[10:11], 11, v[2:3]
	v_or_b32_e32 v2, v36, v40
	global_store_short v[8:9], v0, off
	v_cvt_pk_bf16_f32 v0, v123, s0
	v_lshl_add_u64 v[10:11], v[4:5], 0, v[10:11]
	v_lshlrev_b64 v[12:13], 11, v[2:3]
	v_or_b32_e32 v2, v36, v41
	global_store_short v[10:11], v0, off
	v_cvt_pk_bf16_f32 v0, v122, s0
	v_lshl_add_u64 v[12:13], v[4:5], 0, v[12:13]
	v_lshlrev_b64 v[14:15], 11, v[2:3]
	v_or_b32_e32 v2, v36, v42
	global_store_short v[12:13], v0, off
	v_cvt_pk_bf16_f32 v0, v121, s0
	v_lshl_add_u64 v[14:15], v[4:5], 0, v[14:15]
	v_lshlrev_b64 v[16:17], 11, v[2:3]
	v_or_b32_e32 v2, v36, v43
	global_store_short v[14:15], v0, off
	v_cvt_pk_bf16_f32 v0, v120, s0
	v_lshl_add_u64 v[16:17], v[4:5], 0, v[16:17]
	v_lshlrev_b64 v[18:19], 11, v[2:3]
	v_or_b32_e32 v2, v36, v44
	global_store_short v[16:17], v0, off
	v_cvt_pk_bf16_f32 v0, v119, s0
	v_lshl_add_u64 v[18:19], v[4:5], 0, v[18:19]
	v_lshlrev_b64 v[20:21], 11, v[2:3]
	v_or_b32_e32 v2, v36, v45
	global_store_short v[18:19], v0, off
	v_cvt_pk_bf16_f32 v0, v118, s0
	v_lshl_add_u64 v[20:21], v[4:5], 0, v[20:21]
	v_lshlrev_b64 v[22:23], 11, v[2:3]
	v_or_b32_e32 v2, v36, v46
	global_store_short v[20:21], v0, off
	v_cvt_pk_bf16_f32 v0, v117, s0
	v_lshl_add_u64 v[22:23], v[4:5], 0, v[22:23]
	v_lshlrev_b64 v[24:25], 11, v[2:3]
	v_or_b32_e32 v2, v36, v47
	global_store_short v[22:23], v0, off
	v_cvt_pk_bf16_f32 v0, v116, s0
	v_lshl_add_u64 v[24:25], v[4:5], 0, v[24:25]
	v_lshlrev_b64 v[26:27], 11, v[2:3]
	v_or_b32_e32 v2, v36, v48
	global_store_short v[24:25], v0, off
	v_cvt_pk_bf16_f32 v0, v115, s0
	v_lshl_add_u64 v[26:27], v[4:5], 0, v[26:27]
	v_lshlrev_b64 v[28:29], 11, v[2:3]
	v_or_b32_e32 v2, v36, v49
	global_store_short v[26:27], v0, off
	v_cvt_pk_bf16_f32 v0, v114, s0
	v_lshl_add_u64 v[28:29], v[4:5], 0, v[28:29]
	v_lshlrev_b64 v[30:31], 11, v[2:3]
	v_or_b32_e32 v2, v36, v50
	global_store_short v[28:29], v0, off
	v_cvt_pk_bf16_f32 v0, v113, s0
	v_lshl_add_u64 v[30:31], v[4:5], 0, v[30:31]
	v_lshlrev_b64 v[32:33], 11, v[2:3]
	v_or_b32_e32 v2, v36, v51
	global_store_short v[30:31], v0, off
	v_cvt_pk_bf16_f32 v0, v112, s0
	v_lshl_add_u64 v[32:33], v[4:5], 0, v[32:33]
	v_lshlrev_b64 v[34:35], 11, v[2:3]
	v_or_b32_e32 v2, v36, v52
	global_store_short v[32:33], v0, off
	v_cvt_pk_bf16_f32 v0, v111, s0
	v_lshl_add_u64 v[34:35], v[4:5], 0, v[34:35]
	v_lshlrev_b64 v[2:3], 11, v[2:3]
	global_store_short v[34:35], v0, off
	v_cvt_pk_bf16_f32 v0, v110, s0
	v_lshl_add_u64 v[2:3], v[4:5], 0, v[2:3]
	global_store_short v[2:3], v0, off
	v_cvt_pk_bf16_f32 v0, v109, s0
	global_store_short v[6:7], v0, off offset:64
	v_cvt_pk_bf16_f32 v0, v108, s0
	global_store_short v[8:9], v0, off offset:64
	v_cvt_pk_bf16_f32 v0, v107, s0
	global_store_short v[10:11], v0, off offset:64
	v_cvt_pk_bf16_f32 v0, v106, s0
	global_store_short v[12:13], v0, off offset:64
	v_cvt_pk_bf16_f32 v0, v105, s0
	global_store_short v[14:15], v0, off offset:64
	v_cvt_pk_bf16_f32 v0, v104, s0
	global_store_short v[16:17], v0, off offset:64
	v_cvt_pk_bf16_f32 v0, v103, s0
	global_store_short v[18:19], v0, off offset:64
	v_cvt_pk_bf16_f32 v0, v102, s0
	global_store_short v[20:21], v0, off offset:64
	v_cvt_pk_bf16_f32 v0, v101, s0
	global_store_short v[22:23], v0, off offset:64
	v_cvt_pk_bf16_f32 v0, v100, s0
	global_store_short v[24:25], v0, off offset:64
	v_cvt_pk_bf16_f32 v0, v99, s0
	global_store_short v[26:27], v0, off offset:64
	v_cvt_pk_bf16_f32 v0, v98, s0
	global_store_short v[28:29], v0, off offset:64
	v_cvt_pk_bf16_f32 v0, v97, s0
	global_store_short v[30:31], v0, off offset:64
	v_cvt_pk_bf16_f32 v0, v96, s0
	global_store_short v[32:33], v0, off offset:64
	v_cvt_pk_bf16_f32 v0, v95, s0
	s_add_i32 s31, s31, s58
	s_add_i32 s29, s29, s58
	global_store_short v[34:35], v0, off offset:64
	v_cvt_pk_bf16_f32 v0, v94, s0
	s_cmp_gt_u32 s31, 63
	global_store_short v[2:3], v0, off offset:64
	s_cbranch_scc0 .LBB0_133

; DI u16 f2bf(float x) { return (u16)(pack2(x, 0.f) & 0xffffu); }
; DI int crow(int i, int h) { return (i & 3) + 8 * (i >> 2) + 4 * h; }
; DI void phase_m1(const Params& p, int l, int grp, char* smem) {
;     ...
;       for (int ms = 0; ms < 4; ++ms)
; #pragma unroll
;         for (int i = 0; i < 16; ++i) {
;           const int row = mt * 256 + wm * 128 + ms * 32 + crow(i, lh);
;           const int pos = row & 4095;
;           const float2 cs = t64[pos * 32 + lr];
;           const float x1 = acc[ms][0][i] + bias0, x2 = acc[ms][1][i] + bias1;
;           z[(size_t)row * ZW + cb0 + lr] = f2bf(x1 * cs.x - x2 * cs.y);
;           z[(size_t)row * ZW + cb0 + 32 + lr] = f2bf(x1 * cs.y + x2 * cs.x);
;         }
.LBB0_775:
	s_or_b64 exec, exec, s[0:1]
	s_and_saveexec_b64 s[0:1], s[8:9]
	s_cbranch_execz .LBB0_777
	s_lshl_b32 s6, s39, 8
	v_lshl_add_u32 v0, v168, 7, s6
	v_lshl_or_b32 v136, v167, 2, v0
	v_lshlrev_b32_e32 v0, 1, v169
	v_lshl_add_u64 v[134:135], s[44:45], 0, v[0:1]
	v_lshlrev_b32_e32 v0, 1, v131
	v_lshl_add_u64 v[134:135], v[134:135], 0, v[0:1]
	v_lshlrev_b32_e32 v0, 5, v136
	s_mov_b32 s6, 0x1f080
	v_and_or_b32 v0, v0, s6, v131
	v_lshlrev_b32_e32 v0, 3, v0
	v_lshlrev_b32_e32 v184, 5, v136
	v_and_b32_e32 v184, 0x1f080, v184
	v_or_b32_e32 v184, v184, v131
	v_lshlrev_b32_e32 v184, 3, v184
	global_load_dwordx2 v[144:145], v184, s[4:5]
	v_or_b32_e32 v184, 1, v136
	v_lshlrev_b32_e32 v184, 5, v184
	v_and_b32_e32 v184, 0x1f0a0, v184
	v_or_b32_e32 v184, v184, v131
	v_lshlrev_b32_e32 v184, 3, v184
	global_load_dwordx2 v[146:147], v184, s[4:5]
	v_or_b32_e32 v184, 2, v136
	v_lshlrev_b32_e32 v184, 5, v184
	v_and_b32_e32 v184, 0x1f0c0, v184
	v_or_b32_e32 v184, v184, v131
	v_lshlrev_b32_e32 v184, 3, v184
	global_load_dwordx2 v[148:149], v184, s[4:5]
	v_or_b32_e32 v184, 3, v136
	v_lshlrev_b32_e32 v184, 5, v184
	v_and_b32_e32 v184, 0x1f0e0, v184
	v_or_b32_e32 v184, v184, v131
	v_lshlrev_b32_e32 v184, 3, v184
	global_load_dwordx2 v[150:151], v184, s[4:5]
	v_or_b32_e32 v184, 8, v136
	v_lshlrev_b32_e32 v184, 5, v184
	v_and_b32_e32 v184, 0x1f180, v184
	v_or_b32_e32 v184, v184, v131
	v_lshlrev_b32_e32 v184, 3, v184
	global_load_dwordx2 v[152:153], v184, s[4:5]
	v_or_b32_e32 v184, 9, v136
	v_lshlrev_b32_e32 v184, 5, v184
	v_and_b32_e32 v184, 0x1f1a0, v184
	v_or_b32_e32 v184, v184, v131
	v_lshlrev_b32_e32 v184, 3, v184
	global_load_dwordx2 v[154:155], v184, s[4:5]
	v_or_b32_e32 v184, 10, v136
	v_lshlrev_b32_e32 v184, 5, v184
	v_and_b32_e32 v184, 0x1f1c0, v184
	v_or_b32_e32 v184, v184, v131
	v_lshlrev_b32_e32 v184, 3, v184
	global_load_dwordx2 v[156:157], v184, s[4:5]
	v_or_b32_e32 v184, 11, v136
	v_lshlrev_b32_e32 v184, 5, v184
	v_and_b32_e32 v184, 0x1f1e0, v184
	v_or_b32_e32 v184, v184, v131
	v_lshlrev_b32_e32 v184, 3, v184
	global_load_dwordx2 v[158:159], v184, s[4:5]
	v_or_b32_e32 v184, 16, v136
	v_lshlrev_b32_e32 v184, 5, v184
	v_and_b32_e32 v184, 0x1f280, v184
	v_or_b32_e32 v184, v184, v131
	v_lshlrev_b32_e32 v184, 3, v184
	global_load_dwordx2 v[160:161], v184, s[4:5]
	v_or_b32_e32 v184, 17, v136
	v_lshlrev_b32_e32 v184, 5, v184
	v_and_b32_e32 v184, 0x1f2a0, v184
	v_or_b32_e32 v184, v184, v131
	v_lshlrev_b32_e32 v184, 3, v184
	global_load_dwordx2 v[170:171], v184, s[4:5]
	v_or_b32_e32 v184, 18, v136
	v_lshlrev_b32_e32 v184, 5, v184
	v_and_b32_e32 v184, 0x1f2c0, v184
	v_or_b32_e32 v184, v184, v131
	v_lshlrev_b32_e32 v184, 3, v184
	global_load_dwordx2 v[172:173], v184, s[4:5]
	v_or_b32_e32 v184, 19, v136
	v_lshlrev_b32_e32 v184, 5, v184
	v_and_b32_e32 v184, 0x1f2e0, v184
	v_or_b32_e32 v184, v184, v131
	v_lshlrev_b32_e32 v184, 3, v184
	global_load_dwordx2 v[174:175], v184, s[4:5]
	v_or_b32_e32 v184, 24, v136
	v_lshlrev_b32_e32 v184, 5, v184
	v_and_b32_e32 v184, 0x1f380, v184
	v_or_b32_e32 v184, v184, v131
	v_lshlrev_b32_e32 v184, 3, v184
	global_load_dwordx2 v[176:177], v184, s[4:5]
	v_or_b32_e32 v184, 25, v136
	v_lshlrev_b32_e32 v184, 5, v184
	v_and_b32_e32 v184, 0x1f3a0, v184
	v_or_b32_e32 v184, v184, v131
	v_lshlrev_b32_e32 v184, 3, v184
	global_load_dwordx2 v[178:179], v184, s[4:5]
	v_or_b32_e32 v184, 26, v136
	v_lshlrev_b32_e32 v184, 5, v184
	v_and_b32_e32 v184, 0x1f3c0, v184
	v_or_b32_e32 v184, v184, v131
	v_lshlrev_b32_e32 v184, 3, v184
	global_load_dwordx2 v[180:181], v184, s[4:5]
	v_or_b32_e32 v184, 27, v136
	v_lshlrev_b32_e32 v184, 5, v184
	v_and_b32_e32 v184, 0x1f3e0, v184
	v_or_b32_e32 v184, v184, v131
	v_lshlrev_b32_e32 v184, 3, v184
	global_load_dwordx2 v[182:183], v184, s[4:5]
	s_waitcnt vmcnt(16)
	v_add_f32_e32 v137, v98, v130
	v_add_f32_e32 v0, v114, v132
	s_movk_i32 s8, 0x2200
	s_movk_i32 s82, 0x2200
	s_waitcnt vmcnt(15)
	v_mul_f32_e32 v140, v137, v145
	v_fma_f32 v140, v0, v144, -v140
	v_mul_f32_e32 v0, v0, v145
	v_fmac_f32_e32 v0, v137, v144
	v_cvt_pk_bf16_f32 v142, v140, s0
	v_mad_i64_i32 v[140:141], s[6:7], v136, s8, v[134:135]
	v_cvt_pk_bf16_f32 v0, v0, s0
	global_store_short v[140:141], v0, off offset:64
	v_or_b32_e32 v0, 1, v136
	v_lshlrev_b32_e32 v137, 5, v0
	s_mov_b32 s6, 0x1f0a0
	v_and_or_b32 v137, v137, s6, v131
	global_store_short v[140:141], v142, off
	v_lshlrev_b32_e32 v137, 3, v137
	v_add_f32_e32 v142, v99, v130
	v_add_f32_e32 v137, v115, v132
	s_waitcnt vmcnt(16)
	v_mul_f32_e32 v140, v142, v147
	v_fma_f32 v140, v137, v146, -v140
	v_cvt_pk_bf16_f32 v143, v140, s0
	v_mad_i64_i32 v[140:141], s[6:7], v0, s8, v[134:135]
	v_mul_f32_e32 v0, v137, v147
	v_fmac_f32_e32 v0, v142, v146
	v_cvt_pk_bf16_f32 v0, v0, s0
	global_store_short v[140:141], v0, off offset:64
	v_or_b32_e32 v0, 2, v136
	v_lshlrev_b32_e32 v137, 5, v0
	s_mov_b32 s6, 0x1f0c0
	v_and_or_b32 v137, v137, s6, v131
	global_store_short v[140:141], v143, off
	v_lshlrev_b32_e32 v137, 3, v137
	v_add_f32_e32 v142, v100, v130
	v_add_f32_e32 v137, v116, v132
	s_waitcnt vmcnt(17)
	v_mul_f32_e32 v140, v142, v149
	v_fma_f32 v140, v137, v148, -v140
	v_cvt_pk_bf16_f32 v143, v140, s0
	v_mad_i64_i32 v[140:141], s[6:7], v0, s8, v[134:135]
	v_mul_f32_e32 v0, v137, v149
	v_fmac_f32_e32 v0, v142, v148
	v_cvt_pk_bf16_f32 v0, v0, s0
	global_store_short v[140:141], v0, off offset:64
	v_or_b32_e32 v0, 3, v136
	v_lshlrev_b32_e32 v137, 5, v0
	s_mov_b32 s6, 0x1f0e0
	v_and_or_b32 v137, v137, s6, v131
	global_store_short v[140:141], v143, off
	v_lshlrev_b32_e32 v137, 3, v137
	v_add_f32_e32 v142, v101, v130
	v_add_f32_e32 v137, v117, v132
	s_waitcnt vmcnt(18)
; DI u16 f2bf(float x) { return (u16)(pack2(x, 0.f) & 0xffffu); }
; DI int crow(int i, int h) { return (i & 3) + 8 * (i >> 2) + 4 * h; }
; DI void phase_m1(const Params& p, int l, int grp, char* smem) {
;     ...
;       for (int ms = 0; ms < 4; ++ms)
; #pragma unroll
;         for (int i = 0; i < 16; ++i) {
;           const int row = mt * 256 + wm * 128 + ms * 32 + crow(i, lh);
;           const int pos = row & 4095;
;           const float2 cs = t64[pos * 32 + lr];
;           const float x1 = acc[ms][0][i] + bias0, x2 = acc[ms][1][i] + bias1;
;           z[(size_t)row * ZW + cb0 + lr] = f2bf(x1 * cs.x - x2 * cs.y);
;           z[(size_t)row * ZW + cb0 + 32 + lr] = f2bf(x1 * cs.y + x2 * cs.x);
;         }
	v_mul_f32_e32 v140, v142, v151
	v_fma_f32 v140, v137, v150, -v140
	v_cvt_pk_bf16_f32 v143, v140, s0
	v_mad_i64_i32 v[140:141], s[6:7], v0, s8, v[134:135]
	v_mul_f32_e32 v0, v137, v151
	v_fmac_f32_e32 v0, v142, v150
	v_cvt_pk_bf16_f32 v0, v0, s0
	global_store_short v[140:141], v0, off offset:64
	v_or_b32_e32 v0, 8, v136
	v_lshlrev_b32_e32 v137, 5, v0
	s_mov_b32 s6, 0x1f180
	v_and_or_b32 v137, v137, s6, v131
	global_store_short v[140:141], v143, off
	v_lshlrev_b32_e32 v137, 3, v137
	v_add_f32_e32 v142, v102, v130
	v_add_f32_e32 v137, v118, v132
	s_waitcnt vmcnt(19)
	v_mul_f32_e32 v140, v142, v153
	v_fma_f32 v140, v137, v152, -v140
	v_cvt_pk_bf16_f32 v143, v140, s0
	v_mad_i64_i32 v[140:141], s[6:7], v0, s8, v[134:135]
	v_mul_f32_e32 v0, v137, v153
	v_fmac_f32_e32 v0, v142, v152
	v_cvt_pk_bf16_f32 v0, v0, s0
	global_store_short v[140:141], v0, off offset:64
	v_or_b32_e32 v0, 9, v136
	v_lshlrev_b32_e32 v137, 5, v0
	s_mov_b32 s6, 0x1f1a0
	v_and_or_b32 v137, v137, s6, v131
	global_store_short v[140:141], v143, off
	v_lshlrev_b32_e32 v137, 3, v137
	v_add_f32_e32 v142, v103, v130
	v_add_f32_e32 v137, v119, v132
	s_waitcnt vmcnt(20)
	v_mul_f32_e32 v140, v142, v155
	v_fma_f32 v140, v137, v154, -v140
	v_cvt_pk_bf16_f32 v143, v140, s0
	v_mad_i64_i32 v[140:141], s[6:7], v0, s8, v[134:135]
	v_mul_f32_e32 v0, v137, v155
	v_fmac_f32_e32 v0, v142, v154
	v_cvt_pk_bf16_f32 v0, v0, s0
	global_store_short v[140:141], v0, off offset:64
	v_or_b32_e32 v0, 10, v136
	v_lshlrev_b32_e32 v137, 5, v0
	s_mov_b32 s6, 0x1f1c0
	v_and_or_b32 v137, v137, s6, v131
	global_store_short v[140:141], v143, off
	v_lshlrev_b32_e32 v137, 3, v137
	v_add_f32_e32 v142, v104, v130
	v_add_f32_e32 v137, v120, v132
	s_waitcnt vmcnt(21)
	v_mul_f32_e32 v140, v142, v157
	v_fma_f32 v140, v137, v156, -v140
	v_cvt_pk_bf16_f32 v143, v140, s0
	v_mad_i64_i32 v[140:141], s[6:7], v0, s8, v[134:135]
	v_mul_f32_e32 v0, v137, v157
	v_fmac_f32_e32 v0, v142, v156
	v_cvt_pk_bf16_f32 v0, v0, s0
	global_store_short v[140:141], v0, off offset:64
	v_or_b32_e32 v0, 11, v136
	v_lshlrev_b32_e32 v137, 5, v0
	s_mov_b32 s6, 0x1f1e0
	v_and_or_b32 v137, v137, s6, v131
	global_store_short v[140:141], v143, off
	v_lshlrev_b32_e32 v137, 3, v137
	v_add_f32_e32 v142, v105, v130
	v_add_f32_e32 v137, v121, v132
	s_waitcnt vmcnt(22)
	v_mul_f32_e32 v140, v142, v159
	v_fma_f32 v140, v137, v158, -v140
	v_cvt_pk_bf16_f32 v143, v140, s0
	v_mad_i64_i32 v[140:141], s[6:7], v0, s8, v[134:135]
	v_mul_f32_e32 v0, v137, v159
	v_fmac_f32_e32 v0, v142, v158
	v_cvt_pk_bf16_f32 v0, v0, s0
	global_store_short v[140:141], v0, off offset:64
	v_or_b32_e32 v0, 16, v136
	v_lshlrev_b32_e32 v137, 5, v0
	s_mov_b32 s6, 0x1f280
	v_and_or_b32 v137, v137, s6, v131
	global_store_short v[140:141], v143, off
	v_lshlrev_b32_e32 v137, 3, v137
	v_add_f32_e32 v142, v106, v130
	v_add_f32_e32 v137, v122, v132
	s_waitcnt vmcnt(23)
	v_mul_f32_e32 v140, v142, v161
	v_fma_f32 v140, v137, v160, -v140
	v_cvt_pk_bf16_f32 v143, v140, s0
	v_mad_i64_i32 v[140:141], s[6:7], v0, s8, v[134:135]
	v_mul_f32_e32 v0, v137, v161
	v_fmac_f32_e32 v0, v142, v160
	v_cvt_pk_bf16_f32 v0, v0, s0
	global_store_short v[140:141], v0, off offset:64
	v_or_b32_e32 v0, 17, v136
	v_lshlrev_b32_e32 v137, 5, v0
	s_mov_b32 s6, 0x1f2a0
	v_and_or_b32 v137, v137, s6, v131
	global_store_short v[140:141], v143, off
	v_lshlrev_b32_e32 v137, 3, v137
	v_add_f32_e32 v142, v107, v130
	v_add_f32_e32 v137, v123, v132
	s_waitcnt vmcnt(24)
	v_mul_f32_e32 v140, v142, v171
	v_fma_f32 v140, v137, v170, -v140
	v_cvt_pk_bf16_f32 v143, v140, s0
	v_mad_i64_i32 v[140:141], s[6:7], v0, s8, v[134:135]
	v_mul_f32_e32 v0, v137, v171
	v_fmac_f32_e32 v0, v142, v170
	v_cvt_pk_bf16_f32 v0, v0, s0
	global_store_short v[140:141], v0, off offset:64
	v_or_b32_e32 v0, 18, v136
	v_lshlrev_b32_e32 v137, 5, v0
	s_mov_b32 s6, 0x1f2c0
	v_and_or_b32 v137, v137, s6, v131
	global_store_short v[140:141], v143, off
	v_lshlrev_b32_e32 v137, 3, v137
	v_add_f32_e32 v142, v108, v130
	v_add_f32_e32 v137, v124, v132
	s_waitcnt vmcnt(25)
	v_mul_f32_e32 v140, v142, v173
	v_fma_f32 v140, v137, v172, -v140
	v_cvt_pk_bf16_f32 v143, v140, s0
	v_mad_i64_i32 v[140:141], s[6:7], v0, s8, v[134:135]
	v_mul_f32_e32 v0, v137, v173
	v_fmac_f32_e32 v0, v142, v172
	v_cvt_pk_bf16_f32 v0, v0, s0
	global_store_short v[140:141], v0, off offset:64
	v_or_b32_e32 v0, 19, v136
	v_lshlrev_b32_e32 v137, 5, v0
	s_mov_b32 s6, 0x1f2e0
	v_and_or_b32 v137, v137, s6, v131
	global_store_short v[140:141], v143, off
	v_lshlrev_b32_e32 v137, 3, v137
	v_add_f32_e32 v142, v109, v130
	v_add_f32_e32 v137, v125, v132
	s_waitcnt vmcnt(26)
	v_mul_f32_e32 v140, v142, v175
	v_fma_f32 v140, v137, v174, -v140
	v_cvt_pk_bf16_f32 v143, v140, s0
	v_mad_i64_i32 v[140:141], s[6:7], v0, s8, v[134:135]
	v_mul_f32_e32 v0, v137, v175
	v_fmac_f32_e32 v0, v142, v174
	v_cvt_pk_bf16_f32 v0, v0, s0
	global_store_short v[140:141], v0, off offset:64
	v_or_b32_e32 v0, 24, v136
	v_lshlrev_b32_e32 v137, 5, v0
	s_mov_b32 s6, 0x1f380
	v_and_or_b32 v137, v137, s6, v131
	global_store_short v[140:141], v143, off
	v_lshlrev_b32_e32 v137, 3, v137
	v_add_f32_e32 v142, v110, v130
	v_add_f32_e32 v137, v126, v132
	s_waitcnt vmcnt(27)
	v_mul_f32_e32 v140, v142, v177
	v_fma_f32 v140, v137, v176, -v140
	v_cvt_pk_bf16_f32 v143, v140, s0
	v_mad_i64_i32 v[140:141], s[6:7], v0, s8, v[134:135]
	v_mul_f32_e32 v0, v137, v177
	v_fmac_f32_e32 v0, v142, v176
	v_cvt_pk_bf16_f32 v0, v0, s0
	global_store_short v[140:141], v0, off offset:64
	v_or_b32_e32 v0, 25, v136
	v_lshlrev_b32_e32 v137, 5, v0
	s_mov_b32 s6, 0x1f3a0
	v_and_or_b32 v137, v137, s6, v131
	global_store_short v[140:141], v143, off
	v_lshlrev_b32_e32 v137, 3, v137
	v_add_f32_e32 v142, v111, v130
	v_add_f32_e32 v137, v127, v132
	s_waitcnt vmcnt(28)
; DI u16 f2bf(float x) { return (u16)(pack2(x, 0.f) & 0xffffu); }
; DI int crow(int i, int h) { return (i & 3) + 8 * (i >> 2) + 4 * h; }
; DI void phase_m1(const Params& p, int l, int grp, char* smem) {
;     ...
;       for (int ms = 0; ms < 4; ++ms)
; #pragma unroll
;         for (int i = 0; i < 16; ++i) {
;           const int row = mt * 256 + wm * 128 + ms * 32 + crow(i, lh);
;           const int pos = row & 4095;
;           const float2 cs = t64[pos * 32 + lr];
;           const float x1 = acc[ms][0][i] + bias0, x2 = acc[ms][1][i] + bias1;
;           z[(size_t)row * ZW + cb0 + lr] = f2bf(x1 * cs.x - x2 * cs.y);
;           z[(size_t)row * ZW + cb0 + 32 + lr] = f2bf(x1 * cs.y + x2 * cs.x);
;         }
	v_mul_f32_e32 v140, v142, v179
	v_fma_f32 v140, v137, v178, -v140
	v_cvt_pk_bf16_f32 v143, v140, s0
	v_mad_i64_i32 v[140:141], s[6:7], v0, s8, v[134:135]
	v_mul_f32_e32 v0, v137, v179
	v_fmac_f32_e32 v0, v142, v178
	v_cvt_pk_bf16_f32 v0, v0, s0
	global_store_short v[140:141], v0, off offset:64
	v_or_b32_e32 v0, 26, v136
	v_lshlrev_b32_e32 v137, 5, v0
	s_mov_b32 s6, 0x1f3c0
	v_and_or_b32 v137, v137, s6, v131
	global_store_short v[140:141], v143, off
	v_lshlrev_b32_e32 v137, 3, v137
	v_add_f32_e32 v142, v112, v130
	v_add_f32_e32 v137, v128, v132
	s_waitcnt vmcnt(29)
	v_mul_f32_e32 v140, v142, v181
	v_fma_f32 v140, v137, v180, -v140
	v_cvt_pk_bf16_f32 v143, v140, s0
	v_mad_i64_i32 v[140:141], s[6:7], v0, s8, v[134:135]
	v_mul_f32_e32 v0, v137, v181
	v_fmac_f32_e32 v0, v142, v180
	v_cvt_pk_bf16_f32 v0, v0, s0
	global_store_short v[140:141], v0, off offset:64
	v_or_b32_e32 v0, 27, v136
	v_lshlrev_b32_e32 v137, 5, v0
	s_mov_b32 s6, 0x1f3e0
	v_and_or_b32 v137, v137, s6, v131
	global_store_short v[140:141], v143, off
	v_lshlrev_b32_e32 v137, 3, v137
	v_add_f32_e32 v142, v113, v130
	v_add_f32_e32 v137, v129, v132
	s_waitcnt vmcnt(30)
	v_mul_f32_e32 v140, v142, v183
	v_fma_f32 v140, v137, v182, -v140
	v_cvt_pk_bf16_f32 v143, v140, s0
	v_mad_i64_i32 v[140:141], s[6:7], v0, s8, v[134:135]
	v_mul_f32_e32 v0, v137, v183
	v_fmac_f32_e32 v0, v142, v182
	v_cvt_pk_bf16_f32 v0, v0, s0
	global_store_short v[140:141], v0, off offset:64
	v_or_b32_e32 v0, 32, v136
	v_lshlrev_b32_e32 v137, 5, v0
	s_mov_b32 s6, 0x1f480
	v_and_or_b32 v137, v137, s6, v131
	global_store_short v[140:141], v143, off
	v_lshlrev_b32_e32 v137, 3, v137
	v_or_b32_e32 v184, 32, v136
	v_lshlrev_b32_e32 v184, 5, v184
	v_and_b32_e32 v184, 0x1f480, v184
	v_or_b32_e32 v184, v184, v131
	v_lshlrev_b32_e32 v184, 3, v184
	global_load_dwordx2 v[144:145], v184, s[4:5]
	v_or_b32_e32 v184, 33, v136
	v_lshlrev_b32_e32 v184, 5, v184
	v_and_b32_e32 v184, 0x1f4a0, v184
	v_or_b32_e32 v184, v184, v131
	v_lshlrev_b32_e32 v184, 3, v184
	global_load_dwordx2 v[146:147], v184, s[4:5]
	v_or_b32_e32 v184, 34, v136
	v_lshlrev_b32_e32 v184, 5, v184
	v_and_b32_e32 v184, 0x1f4c0, v184
	v_or_b32_e32 v184, v184, v131
	v_lshlrev_b32_e32 v184, 3, v184
	global_load_dwordx2 v[148:149], v184, s[4:5]
	v_or_b32_e32 v184, 35, v136
	v_lshlrev_b32_e32 v184, 5, v184
	v_and_b32_e32 v184, 0x1f4e0, v184
	v_or_b32_e32 v184, v184, v131
	v_lshlrev_b32_e32 v184, 3, v184
	global_load_dwordx2 v[150:151], v184, s[4:5]
	v_or_b32_e32 v184, 40, v136
	v_lshlrev_b32_e32 v184, 5, v184
	v_and_b32_e32 v184, 0x1f580, v184
	v_or_b32_e32 v184, v184, v131
	v_lshlrev_b32_e32 v184, 3, v184
	global_load_dwordx2 v[152:153], v184, s[4:5]
	v_or_b32_e32 v184, 41, v136
	v_lshlrev_b32_e32 v184, 5, v184
	v_and_b32_e32 v184, 0x1f5a0, v184
	v_or_b32_e32 v184, v184, v131
	v_lshlrev_b32_e32 v184, 3, v184
	global_load_dwordx2 v[154:155], v184, s[4:5]
	v_or_b32_e32 v184, 42, v136
	v_lshlrev_b32_e32 v184, 5, v184
	v_and_b32_e32 v184, 0x1f5c0, v184
	v_or_b32_e32 v184, v184, v131
	v_lshlrev_b32_e32 v184, 3, v184
	global_load_dwordx2 v[156:157], v184, s[4:5]
	v_or_b32_e32 v184, 43, v136
	v_lshlrev_b32_e32 v184, 5, v184
	v_and_b32_e32 v184, 0x1f5e0, v184
	v_or_b32_e32 v184, v184, v131
	v_lshlrev_b32_e32 v184, 3, v184
	global_load_dwordx2 v[158:159], v184, s[4:5]
	v_or_b32_e32 v184, 48, v136
	v_lshlrev_b32_e32 v184, 5, v184
	v_and_b32_e32 v184, 0x1f680, v184
	v_or_b32_e32 v184, v184, v131
	v_lshlrev_b32_e32 v184, 3, v184
	global_load_dwordx2 v[160:161], v184, s[4:5]
	v_or_b32_e32 v184, 49, v136
	v_lshlrev_b32_e32 v184, 5, v184
	v_and_b32_e32 v184, 0x1f6a0, v184
	v_or_b32_e32 v184, v184, v131
	v_lshlrev_b32_e32 v184, 3, v184
	global_load_dwordx2 v[170:171], v184, s[4:5]
	v_or_b32_e32 v184, 50, v136
	v_lshlrev_b32_e32 v184, 5, v184
	v_and_b32_e32 v184, 0x1f6c0, v184
	v_or_b32_e32 v184, v184, v131
	v_lshlrev_b32_e32 v184, 3, v184
	global_load_dwordx2 v[172:173], v184, s[4:5]
	v_or_b32_e32 v184, 51, v136
	v_lshlrev_b32_e32 v184, 5, v184
	v_and_b32_e32 v184, 0x1f6e0, v184
	v_or_b32_e32 v184, v184, v131
	v_lshlrev_b32_e32 v184, 3, v184
	global_load_dwordx2 v[174:175], v184, s[4:5]
	v_or_b32_e32 v184, 56, v136
	v_lshlrev_b32_e32 v184, 5, v184
	v_and_b32_e32 v184, 0x1f780, v184
	v_or_b32_e32 v184, v184, v131
	v_lshlrev_b32_e32 v184, 3, v184
	global_load_dwordx2 v[176:177], v184, s[4:5]
	v_or_b32_e32 v184, 57, v136
	v_lshlrev_b32_e32 v184, 5, v184
	v_and_b32_e32 v184, 0x1f7a0, v184
	v_or_b32_e32 v184, v184, v131
	v_lshlrev_b32_e32 v184, 3, v184
	global_load_dwordx2 v[178:179], v184, s[4:5]
	v_or_b32_e32 v184, 58, v136
	v_lshlrev_b32_e32 v184, 5, v184
	v_and_b32_e32 v184, 0x1f7c0, v184
	v_or_b32_e32 v184, v184, v131
	v_lshlrev_b32_e32 v184, 3, v184
	global_load_dwordx2 v[180:181], v184, s[4:5]
	v_or_b32_e32 v184, 59, v136
	v_lshlrev_b32_e32 v184, 5, v184
	v_and_b32_e32 v184, 0x1f7e0, v184
	v_or_b32_e32 v184, v184, v131
	v_lshlrev_b32_e32 v184, 3, v184
	global_load_dwordx2 v[182:183], v184, s[4:5]
	v_add_f32_e32 v142, v66, v130
	v_add_f32_e32 v137, v82, v132
	s_waitcnt vmcnt(15)
	v_mul_f32_e32 v140, v142, v145
	v_fma_f32 v140, v137, v144, -v140
	v_cvt_pk_bf16_f32 v143, v140, s0
	v_mad_i64_i32 v[140:141], s[6:7], v0, s8, v[134:135]
	v_mul_f32_e32 v0, v137, v145
	v_fmac_f32_e32 v0, v142, v144
	v_cvt_pk_bf16_f32 v0, v0, s0
	global_store_short v[140:141], v0, off offset:64
	v_or_b32_e32 v0, 33, v136
	v_lshlrev_b32_e32 v137, 5, v0
	s_mov_b32 s6, 0x1f4a0
	v_and_or_b32 v137, v137, s6, v131
	global_store_short v[140:141], v143, off
	v_lshlrev_b32_e32 v137, 3, v137
	v_add_f32_e32 v142, v67, v130
	v_add_f32_e32 v137, v83, v132
	s_waitcnt vmcnt(16)
; DI u16 f2bf(float x) { return (u16)(pack2(x, 0.f) & 0xffffu); }
; DI int crow(int i, int h) { return (i & 3) + 8 * (i >> 2) + 4 * h; }
; DI void phase_m1(const Params& p, int l, int grp, char* smem) {
;     ...
;       for (int ms = 0; ms < 4; ++ms)
; #pragma unroll
;         for (int i = 0; i < 16; ++i) {
;           const int row = mt * 256 + wm * 128 + ms * 32 + crow(i, lh);
;           const int pos = row & 4095;
;           const float2 cs = t64[pos * 32 + lr];
;           const float x1 = acc[ms][0][i] + bias0, x2 = acc[ms][1][i] + bias1;
;           z[(size_t)row * ZW + cb0 + lr] = f2bf(x1 * cs.x - x2 * cs.y);
;           z[(size_t)row * ZW + cb0 + 32 + lr] = f2bf(x1 * cs.y + x2 * cs.x);
;         }
	v_mul_f32_e32 v140, v142, v147
	v_fma_f32 v140, v137, v146, -v140
	v_cvt_pk_bf16_f32 v143, v140, s0
	v_mad_i64_i32 v[140:141], s[6:7], v0, s8, v[134:135]
	v_mul_f32_e32 v0, v137, v147
	v_fmac_f32_e32 v0, v142, v146
	v_cvt_pk_bf16_f32 v0, v0, s0
	global_store_short v[140:141], v0, off offset:64
	v_or_b32_e32 v0, 34, v136
	v_lshlrev_b32_e32 v137, 5, v0
	s_mov_b32 s6, 0x1f4c0
	v_and_or_b32 v137, v137, s6, v131
	global_store_short v[140:141], v143, off
	v_lshlrev_b32_e32 v137, 3, v137
	v_add_f32_e32 v142, v68, v130
	v_add_f32_e32 v137, v84, v132
	s_waitcnt vmcnt(17)
	v_mul_f32_e32 v140, v142, v149
	v_fma_f32 v140, v137, v148, -v140
	v_cvt_pk_bf16_f32 v143, v140, s0
	v_mad_i64_i32 v[140:141], s[6:7], v0, s8, v[134:135]
	v_mul_f32_e32 v0, v137, v149
	v_fmac_f32_e32 v0, v142, v148
	v_cvt_pk_bf16_f32 v0, v0, s0
	global_store_short v[140:141], v0, off offset:64
	v_or_b32_e32 v0, 35, v136
	v_lshlrev_b32_e32 v137, 5, v0
	s_mov_b32 s6, 0x1f4e0
	v_and_or_b32 v137, v137, s6, v131
	global_store_short v[140:141], v143, off
	v_lshlrev_b32_e32 v137, 3, v137
	v_add_f32_e32 v142, v69, v130
	v_add_f32_e32 v137, v85, v132
	s_waitcnt vmcnt(18)
	v_mul_f32_e32 v140, v142, v151
	v_fma_f32 v140, v137, v150, -v140
	v_cvt_pk_bf16_f32 v143, v140, s0
	v_mad_i64_i32 v[140:141], s[6:7], v0, s8, v[134:135]
	v_mul_f32_e32 v0, v137, v151
	v_fmac_f32_e32 v0, v142, v150
	v_cvt_pk_bf16_f32 v0, v0, s0
	global_store_short v[140:141], v0, off offset:64
	v_or_b32_e32 v0, 40, v136
	v_lshlrev_b32_e32 v137, 5, v0
	s_mov_b32 s6, 0x1f580
	v_and_or_b32 v137, v137, s6, v131
	global_store_short v[140:141], v143, off
	v_lshlrev_b32_e32 v137, 3, v137
	v_add_f32_e32 v142, v70, v130
	v_add_f32_e32 v137, v86, v132
	s_waitcnt vmcnt(19)
	v_mul_f32_e32 v140, v142, v153
	v_fma_f32 v140, v137, v152, -v140
	v_cvt_pk_bf16_f32 v143, v140, s0
	v_mad_i64_i32 v[140:141], s[6:7], v0, s8, v[134:135]
	v_mul_f32_e32 v0, v137, v153
	v_fmac_f32_e32 v0, v142, v152
	v_cvt_pk_bf16_f32 v0, v0, s0
	global_store_short v[140:141], v0, off offset:64
	v_or_b32_e32 v0, 41, v136
	v_lshlrev_b32_e32 v137, 5, v0
	s_mov_b32 s6, 0x1f5a0
	v_and_or_b32 v137, v137, s6, v131
	global_store_short v[140:141], v143, off
	v_lshlrev_b32_e32 v137, 3, v137
	v_add_f32_e32 v142, v71, v130
	v_add_f32_e32 v137, v87, v132
	s_waitcnt vmcnt(20)
	v_mul_f32_e32 v140, v142, v155
	v_fma_f32 v140, v137, v154, -v140
	v_cvt_pk_bf16_f32 v143, v140, s0
	v_mad_i64_i32 v[140:141], s[6:7], v0, s8, v[134:135]
	v_mul_f32_e32 v0, v137, v155
	v_fmac_f32_e32 v0, v142, v154
	v_cvt_pk_bf16_f32 v0, v0, s0
	global_store_short v[140:141], v0, off offset:64
	v_or_b32_e32 v0, 42, v136
	v_lshlrev_b32_e32 v137, 5, v0
	s_mov_b32 s6, 0x1f5c0
	v_and_or_b32 v137, v137, s6, v131
	global_store_short v[140:141], v143, off
	v_lshlrev_b32_e32 v137, 3, v137
	v_add_f32_e32 v142, v72, v130
	v_add_f32_e32 v137, v88, v132
	s_waitcnt vmcnt(21)
	v_mul_f32_e32 v140, v142, v157
	v_fma_f32 v140, v137, v156, -v140
	v_cvt_pk_bf16_f32 v143, v140, s0
	v_mad_i64_i32 v[140:141], s[6:7], v0, s8, v[134:135]
	v_mul_f32_e32 v0, v137, v157
	v_fmac_f32_e32 v0, v142, v156
	v_cvt_pk_bf16_f32 v0, v0, s0
	global_store_short v[140:141], v0, off offset:64
	v_or_b32_e32 v0, 43, v136
	v_lshlrev_b32_e32 v137, 5, v0
	s_mov_b32 s6, 0x1f5e0
	v_and_or_b32 v137, v137, s6, v131
	global_store_short v[140:141], v143, off
	v_lshlrev_b32_e32 v137, 3, v137
	v_add_f32_e32 v142, v73, v130
	v_add_f32_e32 v137, v89, v132
	s_waitcnt vmcnt(22)
	v_mul_f32_e32 v140, v142, v159
	v_fma_f32 v140, v137, v158, -v140
	v_cvt_pk_bf16_f32 v143, v140, s0
	v_mad_i64_i32 v[140:141], s[6:7], v0, s8, v[134:135]
	v_mul_f32_e32 v0, v137, v159
	v_fmac_f32_e32 v0, v142, v158
	v_cvt_pk_bf16_f32 v0, v0, s0
	global_store_short v[140:141], v0, off offset:64
	v_or_b32_e32 v0, 48, v136
	v_lshlrev_b32_e32 v137, 5, v0
	s_mov_b32 s6, 0x1f680
	v_and_or_b32 v137, v137, s6, v131
	global_store_short v[140:141], v143, off
	v_lshlrev_b32_e32 v137, 3, v137
	v_add_f32_e32 v142, v74, v130
	v_add_f32_e32 v137, v90, v132
	s_waitcnt vmcnt(23)
	v_mul_f32_e32 v140, v142, v161
	v_fma_f32 v140, v137, v160, -v140
	v_cvt_pk_bf16_f32 v143, v140, s0
	v_mad_i64_i32 v[140:141], s[6:7], v0, s8, v[134:135]
	v_mul_f32_e32 v0, v137, v161
	v_fmac_f32_e32 v0, v142, v160
	v_cvt_pk_bf16_f32 v0, v0, s0
	global_store_short v[140:141], v0, off offset:64
	v_or_b32_e32 v0, 49, v136
	v_lshlrev_b32_e32 v137, 5, v0
	s_mov_b32 s6, 0x1f6a0
	v_and_or_b32 v137, v137, s6, v131
	global_store_short v[140:141], v143, off
	v_lshlrev_b32_e32 v137, 3, v137
	v_add_f32_e32 v142, v75, v130
	v_add_f32_e32 v137, v91, v132
	s_waitcnt vmcnt(24)
	v_mul_f32_e32 v140, v142, v171
	v_fma_f32 v140, v137, v170, -v140
	v_cvt_pk_bf16_f32 v143, v140, s0
	v_mad_i64_i32 v[140:141], s[6:7], v0, s8, v[134:135]
	v_mul_f32_e32 v0, v137, v171
	v_fmac_f32_e32 v0, v142, v170
	v_cvt_pk_bf16_f32 v0, v0, s0
	global_store_short v[140:141], v0, off offset:64
	v_or_b32_e32 v0, 50, v136
	v_lshlrev_b32_e32 v137, 5, v0
	s_mov_b32 s6, 0x1f6c0
	v_and_or_b32 v137, v137, s6, v131
	global_store_short v[140:141], v143, off
	v_lshlrev_b32_e32 v137, 3, v137
	v_add_f32_e32 v142, v76, v130
	v_add_f32_e32 v137, v92, v132
	s_waitcnt vmcnt(25)
	v_mul_f32_e32 v140, v142, v173
	v_fma_f32 v140, v137, v172, -v140
	v_cvt_pk_bf16_f32 v143, v140, s0
	v_mad_i64_i32 v[140:141], s[6:7], v0, s8, v[134:135]
	v_mul_f32_e32 v0, v137, v173
	v_fmac_f32_e32 v0, v142, v172
	v_cvt_pk_bf16_f32 v0, v0, s0
	global_store_short v[140:141], v0, off offset:64
	v_or_b32_e32 v0, 51, v136
	v_lshlrev_b32_e32 v137, 5, v0
	s_mov_b32 s6, 0x1f6e0
	v_and_or_b32 v137, v137, s6, v131
	global_store_short v[140:141], v143, off
	v_lshlrev_b32_e32 v137, 3, v137
	v_add_f32_e32 v142, v77, v130
	v_add_f32_e32 v137, v93, v132
	s_waitcnt vmcnt(26)
; DI u16 f2bf(float x) { return (u16)(pack2(x, 0.f) & 0xffffu); }
; DI int crow(int i, int h) { return (i & 3) + 8 * (i >> 2) + 4 * h; }
; DI void phase_m1(const Params& p, int l, int grp, char* smem) {
;     ...
;       for (int ms = 0; ms < 4; ++ms)
; #pragma unroll
;         for (int i = 0; i < 16; ++i) {
;           const int row = mt * 256 + wm * 128 + ms * 32 + crow(i, lh);
;           const int pos = row & 4095;
;           const float2 cs = t64[pos * 32 + lr];
;           const float x1 = acc[ms][0][i] + bias0, x2 = acc[ms][1][i] + bias1;
;           z[(size_t)row * ZW + cb0 + lr] = f2bf(x1 * cs.x - x2 * cs.y);
;           z[(size_t)row * ZW + cb0 + 32 + lr] = f2bf(x1 * cs.y + x2 * cs.x);
;         }
	v_mul_f32_e32 v140, v142, v175
	v_fma_f32 v140, v137, v174, -v140
	v_cvt_pk_bf16_f32 v143, v140, s0
	v_mad_i64_i32 v[140:141], s[6:7], v0, s8, v[134:135]
	v_mul_f32_e32 v0, v137, v175
	v_fmac_f32_e32 v0, v142, v174
	v_cvt_pk_bf16_f32 v0, v0, s0
	global_store_short v[140:141], v0, off offset:64
	v_or_b32_e32 v0, 56, v136
	v_lshlrev_b32_e32 v137, 5, v0
	s_mov_b32 s6, 0x1f780
	v_and_or_b32 v137, v137, s6, v131
	global_store_short v[140:141], v143, off
	v_lshlrev_b32_e32 v137, 3, v137
	v_add_f32_e32 v142, v78, v130
	v_add_f32_e32 v137, v94, v132
	s_waitcnt vmcnt(27)
	v_mul_f32_e32 v140, v142, v177
	v_fma_f32 v140, v137, v176, -v140
	v_cvt_pk_bf16_f32 v143, v140, s0
	v_mad_i64_i32 v[140:141], s[6:7], v0, s8, v[134:135]
	v_mul_f32_e32 v0, v137, v177
	v_fmac_f32_e32 v0, v142, v176
	v_cvt_pk_bf16_f32 v0, v0, s0
	global_store_short v[140:141], v0, off offset:64
	v_or_b32_e32 v0, 57, v136
	v_lshlrev_b32_e32 v137, 5, v0
	s_mov_b32 s6, 0x1f7a0
	v_and_or_b32 v137, v137, s6, v131
	global_store_short v[140:141], v143, off
	v_lshlrev_b32_e32 v137, 3, v137
	v_add_f32_e32 v142, v79, v130
	v_add_f32_e32 v137, v95, v132
	s_waitcnt vmcnt(28)
	v_mul_f32_e32 v140, v142, v179
	v_fma_f32 v140, v137, v178, -v140
	v_cvt_pk_bf16_f32 v143, v140, s0
	v_mad_i64_i32 v[140:141], s[6:7], v0, s8, v[134:135]
	v_mul_f32_e32 v0, v137, v179
	v_fmac_f32_e32 v0, v142, v178
	v_cvt_pk_bf16_f32 v0, v0, s0
	global_store_short v[140:141], v0, off offset:64
	v_or_b32_e32 v0, 58, v136
	v_lshlrev_b32_e32 v137, 5, v0
	s_mov_b32 s6, 0x1f7c0
	v_and_or_b32 v137, v137, s6, v131
	global_store_short v[140:141], v143, off
	v_lshlrev_b32_e32 v137, 3, v137
	v_add_f32_e32 v142, v80, v130
	v_add_f32_e32 v137, v96, v132
	s_waitcnt vmcnt(29)
	v_mul_f32_e32 v140, v142, v181
	v_fma_f32 v140, v137, v180, -v140
	v_cvt_pk_bf16_f32 v143, v140, s0
	v_mad_i64_i32 v[140:141], s[6:7], v0, s8, v[134:135]
	v_mul_f32_e32 v0, v137, v181
	v_fmac_f32_e32 v0, v142, v180
	v_cvt_pk_bf16_f32 v0, v0, s0
	global_store_short v[140:141], v0, off offset:64
	v_or_b32_e32 v0, 59, v136
	v_lshlrev_b32_e32 v137, 5, v0
	s_mov_b32 s6, 0x1f7e0
	v_and_or_b32 v137, v137, s6, v131
	global_store_short v[140:141], v143, off
	v_lshlrev_b32_e32 v137, 3, v137
	v_add_f32_e32 v142, v81, v130
	v_add_f32_e32 v137, v97, v132
	s_waitcnt vmcnt(30)
	v_mul_f32_e32 v140, v142, v183
	v_fma_f32 v140, v137, v182, -v140
	v_cvt_pk_bf16_f32 v143, v140, s0
	v_mad_i64_i32 v[140:141], s[6:7], v0, s8, v[134:135]
	v_mul_f32_e32 v0, v137, v183
	v_fmac_f32_e32 v0, v142, v182
	v_cvt_pk_bf16_f32 v0, v0, s0
	global_store_short v[140:141], v0, off offset:64
	v_or_b32_e32 v0, 64, v136
	v_lshlrev_b32_e32 v137, 5, v0
	s_mov_b32 s6, 0x1f880
	v_and_or_b32 v137, v137, s6, v131
	global_store_short v[140:141], v143, off
	v_lshlrev_b32_e32 v137, 3, v137
	v_or_b32_e32 v184, 64, v136
	v_lshlrev_b32_e32 v184, 5, v184
	v_and_b32_e32 v184, 0x1f880, v184
	v_or_b32_e32 v184, v184, v131
	v_lshlrev_b32_e32 v184, 3, v184
	global_load_dwordx2 v[144:145], v184, s[4:5]
	v_or_b32_e32 v184, 65, v136
	v_lshlrev_b32_e32 v184, 5, v184
	v_and_b32_e32 v184, 0x1f8a0, v184
	v_or_b32_e32 v184, v184, v131
	v_lshlrev_b32_e32 v184, 3, v184
	global_load_dwordx2 v[146:147], v184, s[4:5]
	v_or_b32_e32 v184, 66, v136
	v_lshlrev_b32_e32 v184, 5, v184
	v_and_b32_e32 v184, 0x1f8c0, v184
	v_or_b32_e32 v184, v184, v131
	v_lshlrev_b32_e32 v184, 3, v184
	global_load_dwordx2 v[148:149], v184, s[4:5]
	v_or_b32_e32 v184, 67, v136
	v_lshlrev_b32_e32 v184, 5, v184
	v_and_b32_e32 v184, 0x1f8e0, v184
	v_or_b32_e32 v184, v184, v131
	v_lshlrev_b32_e32 v184, 3, v184
	global_load_dwordx2 v[150:151], v184, s[4:5]
	v_or_b32_e32 v184, 72, v136
	v_lshlrev_b32_e32 v184, 5, v184
	v_and_b32_e32 v184, 0x1f980, v184
	v_or_b32_e32 v184, v184, v131
	v_lshlrev_b32_e32 v184, 3, v184
	global_load_dwordx2 v[152:153], v184, s[4:5]
	v_or_b32_e32 v184, 73, v136
	v_lshlrev_b32_e32 v184, 5, v184
	v_and_b32_e32 v184, 0x1f9a0, v184
	v_or_b32_e32 v184, v184, v131
	v_lshlrev_b32_e32 v184, 3, v184
	global_load_dwordx2 v[154:155], v184, s[4:5]
	v_or_b32_e32 v184, 74, v136
	v_lshlrev_b32_e32 v184, 5, v184
	v_and_b32_e32 v184, 0x1f9c0, v184
	v_or_b32_e32 v184, v184, v131
	v_lshlrev_b32_e32 v184, 3, v184
	global_load_dwordx2 v[156:157], v184, s[4:5]
	v_or_b32_e32 v184, 75, v136
	v_lshlrev_b32_e32 v184, 5, v184
	v_and_b32_e32 v184, 0x1f9e0, v184
	v_or_b32_e32 v184, v184, v131
	v_lshlrev_b32_e32 v184, 3, v184
	global_load_dwordx2 v[158:159], v184, s[4:5]
	v_or_b32_e32 v184, 80, v136
	v_lshlrev_b32_e32 v184, 5, v184
	v_and_b32_e32 v184, 0x1fa80, v184
	v_or_b32_e32 v184, v184, v131
	v_lshlrev_b32_e32 v184, 3, v184
	global_load_dwordx2 v[160:161], v184, s[4:5]
	v_or_b32_e32 v184, 81, v136
	v_lshlrev_b32_e32 v184, 5, v184
	v_and_b32_e32 v184, 0x1faa0, v184
	v_or_b32_e32 v184, v184, v131
	v_lshlrev_b32_e32 v184, 3, v184
	global_load_dwordx2 v[170:171], v184, s[4:5]
	v_or_b32_e32 v184, 82, v136
	v_lshlrev_b32_e32 v184, 5, v184
	v_and_b32_e32 v184, 0x1fac0, v184
	v_or_b32_e32 v184, v184, v131
	v_lshlrev_b32_e32 v184, 3, v184
	global_load_dwordx2 v[172:173], v184, s[4:5]
	v_or_b32_e32 v184, 83, v136
	v_lshlrev_b32_e32 v184, 5, v184
	v_and_b32_e32 v184, 0x1fae0, v184
	v_or_b32_e32 v184, v184, v131
	v_lshlrev_b32_e32 v184, 3, v184
	global_load_dwordx2 v[174:175], v184, s[4:5]
	v_or_b32_e32 v184, 88, v136
	v_lshlrev_b32_e32 v184, 5, v184
	v_and_b32_e32 v184, 0x1fb80, v184
	v_or_b32_e32 v184, v184, v131
	v_lshlrev_b32_e32 v184, 3, v184
	global_load_dwordx2 v[176:177], v184, s[4:5]
	v_or_b32_e32 v184, 89, v136
	v_lshlrev_b32_e32 v184, 5, v184
	v_and_b32_e32 v184, 0x1fba0, v184
	v_or_b32_e32 v184, v184, v131
	v_lshlrev_b32_e32 v184, 3, v184
	global_load_dwordx2 v[178:179], v184, s[4:5]
	v_or_b32_e32 v184, 90, v136
	v_lshlrev_b32_e32 v184, 5, v184
	v_and_b32_e32 v184, 0x1fbc0, v184
	v_or_b32_e32 v184, v184, v131
	v_lshlrev_b32_e32 v184, 3, v184
	global_load_dwordx2 v[180:181], v184, s[4:5]
	v_or_b32_e32 v184, 91, v136
	v_lshlrev_b32_e32 v184, 5, v184
	v_and_b32_e32 v184, 0x1fbe0, v184
	v_or_b32_e32 v184, v184, v131
	v_lshlrev_b32_e32 v184, 3, v184
	global_load_dwordx2 v[182:183], v184, s[4:5]
	v_add_f32_e32 v142, v34, v130
	v_add_f32_e32 v137, v50, v132
	s_waitcnt vmcnt(15)
; DI u16 f2bf(float x) { return (u16)(pack2(x, 0.f) & 0xffffu); }
; DI int crow(int i, int h) { return (i & 3) + 8 * (i >> 2) + 4 * h; }
; DI void phase_m1(const Params& p, int l, int grp, char* smem) {
;     ...
;       for (int ms = 0; ms < 4; ++ms)
; #pragma unroll
;         for (int i = 0; i < 16; ++i) {
;           const int row = mt * 256 + wm * 128 + ms * 32 + crow(i, lh);
;           const int pos = row & 4095;
;           const float2 cs = t64[pos * 32 + lr];
;           const float x1 = acc[ms][0][i] + bias0, x2 = acc[ms][1][i] + bias1;
;           z[(size_t)row * ZW + cb0 + lr] = f2bf(x1 * cs.x - x2 * cs.y);
;           z[(size_t)row * ZW + cb0 + 32 + lr] = f2bf(x1 * cs.y + x2 * cs.x);
;         }
	v_mul_f32_e32 v140, v142, v145
	v_fma_f32 v140, v137, v144, -v140
	v_cvt_pk_bf16_f32 v143, v140, s0
	v_mad_i64_i32 v[140:141], s[6:7], v0, s8, v[134:135]
	v_mul_f32_e32 v0, v137, v145
	v_fmac_f32_e32 v0, v142, v144
	v_cvt_pk_bf16_f32 v0, v0, s0
	global_store_short v[140:141], v0, off offset:64
	v_or_b32_e32 v0, 0x41, v136
	v_lshlrev_b32_e32 v137, 5, v0
	s_mov_b32 s6, 0x1f8a0
	v_and_or_b32 v137, v137, s6, v131
	global_store_short v[140:141], v143, off
	v_lshlrev_b32_e32 v137, 3, v137
	v_add_f32_e32 v142, v35, v130
	v_add_f32_e32 v137, v51, v132
	s_waitcnt vmcnt(16)
	v_mul_f32_e32 v140, v142, v147
	v_fma_f32 v140, v137, v146, -v140
	v_cvt_pk_bf16_f32 v143, v140, s0
	v_mad_i64_i32 v[140:141], s[6:7], v0, s8, v[134:135]
	v_mul_f32_e32 v0, v137, v147
	v_fmac_f32_e32 v0, v142, v146
	v_cvt_pk_bf16_f32 v0, v0, s0
	global_store_short v[140:141], v0, off offset:64
	v_or_b32_e32 v0, 0x42, v136
	v_lshlrev_b32_e32 v137, 5, v0
	s_mov_b32 s6, 0x1f8c0
	v_and_or_b32 v137, v137, s6, v131
	global_store_short v[140:141], v143, off
	v_lshlrev_b32_e32 v137, 3, v137
	v_add_f32_e32 v142, v36, v130
	v_add_f32_e32 v137, v52, v132
	s_waitcnt vmcnt(17)
	v_mul_f32_e32 v140, v142, v149
	v_fma_f32 v140, v137, v148, -v140
	v_cvt_pk_bf16_f32 v143, v140, s0
	v_mad_i64_i32 v[140:141], s[6:7], v0, s8, v[134:135]
	v_mul_f32_e32 v0, v137, v149
	v_fmac_f32_e32 v0, v142, v148
	v_cvt_pk_bf16_f32 v0, v0, s0
	global_store_short v[140:141], v0, off offset:64
	v_or_b32_e32 v0, 0x43, v136
	v_lshlrev_b32_e32 v137, 5, v0
	s_mov_b32 s6, 0x1f8e0
	v_and_or_b32 v137, v137, s6, v131
	global_store_short v[140:141], v143, off
	v_lshlrev_b32_e32 v137, 3, v137
	v_add_f32_e32 v142, v37, v130
	v_add_f32_e32 v137, v53, v132
	s_waitcnt vmcnt(18)
	v_mul_f32_e32 v140, v142, v151
	v_fma_f32 v140, v137, v150, -v140
	v_cvt_pk_bf16_f32 v143, v140, s0
	v_mad_i64_i32 v[140:141], s[6:7], v0, s8, v[134:135]
	v_mul_f32_e32 v0, v137, v151
	v_fmac_f32_e32 v0, v142, v150
	v_cvt_pk_bf16_f32 v0, v0, s0
	global_store_short v[140:141], v0, off offset:64
	v_or_b32_e32 v0, 0x48, v136
	v_lshlrev_b32_e32 v137, 5, v0
	s_mov_b32 s6, 0x1f980
	v_and_or_b32 v137, v137, s6, v131
	global_store_short v[140:141], v143, off
	v_lshlrev_b32_e32 v137, 3, v137
	v_add_f32_e32 v142, v38, v130
	v_add_f32_e32 v137, v54, v132
	s_waitcnt vmcnt(19)
	v_mul_f32_e32 v140, v142, v153
	v_fma_f32 v140, v137, v152, -v140
	v_cvt_pk_bf16_f32 v143, v140, s0
	v_mad_i64_i32 v[140:141], s[6:7], v0, s8, v[134:135]
	v_mul_f32_e32 v0, v137, v153
	v_fmac_f32_e32 v0, v142, v152
	v_cvt_pk_bf16_f32 v0, v0, s0
	global_store_short v[140:141], v0, off offset:64
	v_or_b32_e32 v0, 0x49, v136
	v_lshlrev_b32_e32 v137, 5, v0
	s_mov_b32 s6, 0x1f9a0
	v_and_or_b32 v137, v137, s6, v131
	global_store_short v[140:141], v143, off
	v_lshlrev_b32_e32 v137, 3, v137
	v_add_f32_e32 v142, v39, v130
	v_add_f32_e32 v137, v55, v132
	s_waitcnt vmcnt(20)
	v_mul_f32_e32 v140, v142, v155
	v_fma_f32 v140, v137, v154, -v140
	v_cvt_pk_bf16_f32 v143, v140, s0
	v_mad_i64_i32 v[140:141], s[6:7], v0, s8, v[134:135]
	v_mul_f32_e32 v0, v137, v155
	v_fmac_f32_e32 v0, v142, v154
	v_cvt_pk_bf16_f32 v0, v0, s0
	global_store_short v[140:141], v0, off offset:64
	v_or_b32_e32 v0, 0x4a, v136
	v_lshlrev_b32_e32 v137, 5, v0
	s_mov_b32 s6, 0x1f9c0
	v_and_or_b32 v137, v137, s6, v131
	global_store_short v[140:141], v143, off
	v_lshlrev_b32_e32 v137, 3, v137
	v_add_f32_e32 v142, v40, v130
	v_add_f32_e32 v137, v56, v132
	s_waitcnt vmcnt(21)
	v_mul_f32_e32 v140, v142, v157
	v_fma_f32 v140, v137, v156, -v140
	v_cvt_pk_bf16_f32 v143, v140, s0
	v_mad_i64_i32 v[140:141], s[6:7], v0, s8, v[134:135]
	v_mul_f32_e32 v0, v137, v157
	v_fmac_f32_e32 v0, v142, v156
	v_cvt_pk_bf16_f32 v0, v0, s0
	global_store_short v[140:141], v0, off offset:64
	v_or_b32_e32 v0, 0x4b, v136
	v_lshlrev_b32_e32 v137, 5, v0
	s_mov_b32 s6, 0x1f9e0
	v_and_or_b32 v137, v137, s6, v131
	global_store_short v[140:141], v143, off
	v_lshlrev_b32_e32 v137, 3, v137
	v_add_f32_e32 v142, v41, v130
	v_add_f32_e32 v137, v57, v132
	s_waitcnt vmcnt(22)
	v_mul_f32_e32 v140, v142, v159
	v_fma_f32 v140, v137, v158, -v140
	v_cvt_pk_bf16_f32 v143, v140, s0
	v_mad_i64_i32 v[140:141], s[6:7], v0, s8, v[134:135]
	v_mul_f32_e32 v0, v137, v159
	v_fmac_f32_e32 v0, v142, v158
	v_cvt_pk_bf16_f32 v0, v0, s0
	global_store_short v[140:141], v0, off offset:64
	v_or_b32_e32 v0, 0x50, v136
	v_lshlrev_b32_e32 v137, 5, v0
	s_mov_b32 s6, 0x1fa80
	v_and_or_b32 v137, v137, s6, v131
	global_store_short v[140:141], v143, off
	v_lshlrev_b32_e32 v137, 3, v137
	v_add_f32_e32 v142, v42, v130
	v_add_f32_e32 v137, v58, v132
	s_waitcnt vmcnt(23)
	v_mul_f32_e32 v140, v142, v161
	v_fma_f32 v140, v137, v160, -v140
	v_cvt_pk_bf16_f32 v143, v140, s0
	v_mad_i64_i32 v[140:141], s[6:7], v0, s8, v[134:135]
	v_mul_f32_e32 v0, v137, v161
	v_fmac_f32_e32 v0, v142, v160
	v_cvt_pk_bf16_f32 v0, v0, s0
	global_store_short v[140:141], v0, off offset:64
	v_or_b32_e32 v0, 0x51, v136
	v_lshlrev_b32_e32 v137, 5, v0
	s_mov_b32 s6, 0x1faa0
	v_and_or_b32 v137, v137, s6, v131
	global_store_short v[140:141], v143, off
	v_lshlrev_b32_e32 v137, 3, v137
	v_add_f32_e32 v142, v43, v130
	v_add_f32_e32 v137, v59, v132
	s_waitcnt vmcnt(24)
	v_mul_f32_e32 v140, v142, v171
	v_fma_f32 v140, v137, v170, -v140
	v_cvt_pk_bf16_f32 v143, v140, s0
	v_mad_i64_i32 v[140:141], s[6:7], v0, s8, v[134:135]
	v_mul_f32_e32 v0, v137, v171
	v_fmac_f32_e32 v0, v142, v170
	v_cvt_pk_bf16_f32 v0, v0, s0
	global_store_short v[140:141], v0, off offset:64
	v_or_b32_e32 v0, 0x52, v136
	v_lshlrev_b32_e32 v137, 5, v0
	s_mov_b32 s6, 0x1fac0
	v_and_or_b32 v137, v137, s6, v131
	global_store_short v[140:141], v143, off
	v_lshlrev_b32_e32 v137, 3, v137
	v_add_f32_e32 v142, v44, v130
	v_add_f32_e32 v137, v60, v132
	s_waitcnt vmcnt(25)
; DI u16 f2bf(float x) { return (u16)(pack2(x, 0.f) & 0xffffu); }
; DI int crow(int i, int h) { return (i & 3) + 8 * (i >> 2) + 4 * h; }
; DI void phase_m1(const Params& p, int l, int grp, char* smem) {
;     ...
;       for (int ms = 0; ms < 4; ++ms)
; #pragma unroll
;         for (int i = 0; i < 16; ++i) {
;           const int row = mt * 256 + wm * 128 + ms * 32 + crow(i, lh);
;           const int pos = row & 4095;
;           const float2 cs = t64[pos * 32 + lr];
;           const float x1 = acc[ms][0][i] + bias0, x2 = acc[ms][1][i] + bias1;
;           z[(size_t)row * ZW + cb0 + lr] = f2bf(x1 * cs.x - x2 * cs.y);
;           z[(size_t)row * ZW + cb0 + 32 + lr] = f2bf(x1 * cs.y + x2 * cs.x);
;         }
	v_mul_f32_e32 v140, v142, v173
	v_fma_f32 v140, v137, v172, -v140
	v_cvt_pk_bf16_f32 v143, v140, s0
	v_mad_i64_i32 v[140:141], s[6:7], v0, s8, v[134:135]
	v_mul_f32_e32 v0, v137, v173
	v_fmac_f32_e32 v0, v142, v172
	v_cvt_pk_bf16_f32 v0, v0, s0
	global_store_short v[140:141], v0, off offset:64
	v_or_b32_e32 v0, 0x53, v136
	v_lshlrev_b32_e32 v137, 5, v0
	s_mov_b32 s6, 0x1fae0
	v_and_or_b32 v137, v137, s6, v131
	global_store_short v[140:141], v143, off
	v_lshlrev_b32_e32 v137, 3, v137
	v_add_f32_e32 v142, v45, v130
	v_add_f32_e32 v137, v61, v132
	s_waitcnt vmcnt(26)
	v_mul_f32_e32 v140, v142, v175
	v_fma_f32 v140, v137, v174, -v140
	v_cvt_pk_bf16_f32 v143, v140, s0
	v_mad_i64_i32 v[140:141], s[6:7], v0, s8, v[134:135]
	v_mul_f32_e32 v0, v137, v175
	v_fmac_f32_e32 v0, v142, v174
	v_cvt_pk_bf16_f32 v0, v0, s0
	global_store_short v[140:141], v0, off offset:64
	v_or_b32_e32 v0, 0x58, v136
	v_lshlrev_b32_e32 v137, 5, v0
	s_mov_b32 s6, 0x1fb80
	v_and_or_b32 v137, v137, s6, v131
	global_store_short v[140:141], v143, off
	v_lshlrev_b32_e32 v137, 3, v137
	v_add_f32_e32 v142, v46, v130
	v_add_f32_e32 v137, v62, v132
	s_waitcnt vmcnt(27)
	v_mul_f32_e32 v140, v142, v177
	v_fma_f32 v140, v137, v176, -v140
	v_cvt_pk_bf16_f32 v143, v140, s0
	v_mad_i64_i32 v[140:141], s[6:7], v0, s8, v[134:135]
	v_mul_f32_e32 v0, v137, v177
	v_fmac_f32_e32 v0, v142, v176
	v_cvt_pk_bf16_f32 v0, v0, s0
	global_store_short v[140:141], v0, off offset:64
	v_or_b32_e32 v0, 0x59, v136
	v_lshlrev_b32_e32 v137, 5, v0
	s_mov_b32 s6, 0x1fba0
	v_and_or_b32 v137, v137, s6, v131
	global_store_short v[140:141], v143, off
	v_lshlrev_b32_e32 v137, 3, v137
	v_add_f32_e32 v142, v47, v130
	v_add_f32_e32 v137, v63, v132
	s_waitcnt vmcnt(28)
	v_mul_f32_e32 v140, v142, v179
	v_fma_f32 v140, v137, v178, -v140
	v_cvt_pk_bf16_f32 v143, v140, s0
	v_mad_i64_i32 v[140:141], s[6:7], v0, s8, v[134:135]
	v_mul_f32_e32 v0, v137, v179
	v_fmac_f32_e32 v0, v142, v178
	v_cvt_pk_bf16_f32 v0, v0, s0
	global_store_short v[140:141], v0, off offset:64
	v_or_b32_e32 v0, 0x5a, v136
	v_lshlrev_b32_e32 v137, 5, v0
	s_mov_b32 s6, 0x1fbc0
	v_and_or_b32 v137, v137, s6, v131
	global_store_short v[140:141], v143, off
	v_lshlrev_b32_e32 v137, 3, v137
	v_add_f32_e32 v142, v48, v130
	v_add_f32_e32 v137, v64, v132
	s_waitcnt vmcnt(29)
	v_mul_f32_e32 v140, v142, v181
	v_fma_f32 v140, v137, v180, -v140
	v_cvt_pk_bf16_f32 v143, v140, s0
	v_mad_i64_i32 v[140:141], s[6:7], v0, s8, v[134:135]
	v_mul_f32_e32 v0, v137, v181
	v_fmac_f32_e32 v0, v142, v180
	v_cvt_pk_bf16_f32 v0, v0, s0
	global_store_short v[140:141], v0, off offset:64
	v_or_b32_e32 v0, 0x5b, v136
	v_lshlrev_b32_e32 v137, 5, v0
	s_mov_b32 s6, 0x1fbe0
	v_and_or_b32 v137, v137, s6, v131
	global_store_short v[140:141], v143, off
	v_lshlrev_b32_e32 v137, 3, v137
	v_add_f32_e32 v142, v49, v130
	v_add_f32_e32 v137, v65, v132
	s_waitcnt vmcnt(30)
	v_mul_f32_e32 v140, v142, v183
	v_fma_f32 v140, v137, v182, -v140
	v_cvt_pk_bf16_f32 v143, v140, s0
	v_mad_i64_i32 v[140:141], s[6:7], v0, s8, v[134:135]
	v_mul_f32_e32 v0, v137, v183
	v_fmac_f32_e32 v0, v142, v182
	v_cvt_pk_bf16_f32 v0, v0, s0
	global_store_short v[140:141], v0, off offset:64
	v_or_b32_e32 v0, 0x60, v136
	v_lshlrev_b32_e32 v137, 5, v0
	s_mov_b32 s6, 0x1fc80
	v_and_or_b32 v137, v137, s6, v131
	global_store_short v[140:141], v143, off
	v_lshlrev_b32_e32 v137, 3, v137
	v_or_b32_e32 v184, 96, v136
	v_lshlrev_b32_e32 v184, 5, v184
	v_and_b32_e32 v184, 0x1fc80, v184
	v_or_b32_e32 v184, v184, v131
	v_lshlrev_b32_e32 v184, 3, v184
	global_load_dwordx2 v[144:145], v184, s[4:5]
	v_or_b32_e32 v184, 97, v136
	v_lshlrev_b32_e32 v184, 5, v184
	v_and_b32_e32 v184, 0x1fca0, v184
	v_or_b32_e32 v184, v184, v131
	v_lshlrev_b32_e32 v184, 3, v184
	global_load_dwordx2 v[146:147], v184, s[4:5]
	v_or_b32_e32 v184, 98, v136
	v_lshlrev_b32_e32 v184, 5, v184
	v_and_b32_e32 v184, 0x1fcc0, v184
	v_or_b32_e32 v184, v184, v131
	v_lshlrev_b32_e32 v184, 3, v184
	global_load_dwordx2 v[148:149], v184, s[4:5]
	v_or_b32_e32 v184, 99, v136
	v_lshlrev_b32_e32 v184, 5, v184
	v_and_b32_e32 v184, 0x1fce0, v184
	v_or_b32_e32 v184, v184, v131
	v_lshlrev_b32_e32 v184, 3, v184
	global_load_dwordx2 v[150:151], v184, s[4:5]
	v_or_b32_e32 v184, 104, v136
	v_lshlrev_b32_e32 v184, 5, v184
	v_and_b32_e32 v184, 0x1fd80, v184
	v_or_b32_e32 v184, v184, v131
	v_lshlrev_b32_e32 v184, 3, v184
	global_load_dwordx2 v[152:153], v184, s[4:5]
	v_or_b32_e32 v184, 105, v136
	v_lshlrev_b32_e32 v184, 5, v184
	v_and_b32_e32 v184, 0x1fda0, v184
	v_or_b32_e32 v184, v184, v131
	v_lshlrev_b32_e32 v184, 3, v184
	global_load_dwordx2 v[154:155], v184, s[4:5]
	v_or_b32_e32 v184, 106, v136
	v_lshlrev_b32_e32 v184, 5, v184
	v_and_b32_e32 v184, 0x1fdc0, v184
	v_or_b32_e32 v184, v184, v131
	v_lshlrev_b32_e32 v184, 3, v184
	global_load_dwordx2 v[156:157], v184, s[4:5]
	v_or_b32_e32 v184, 107, v136
	v_lshlrev_b32_e32 v184, 5, v184
	v_and_b32_e32 v184, 0x1fde0, v184
	v_or_b32_e32 v184, v184, v131
	v_lshlrev_b32_e32 v184, 3, v184
	global_load_dwordx2 v[158:159], v184, s[4:5]
	v_or_b32_e32 v184, 112, v136
	v_lshlrev_b32_e32 v184, 5, v184
	v_and_b32_e32 v184, 0x1fe80, v184
	v_or_b32_e32 v184, v184, v131
	v_lshlrev_b32_e32 v184, 3, v184
	global_load_dwordx2 v[160:161], v184, s[4:5]
	v_or_b32_e32 v184, 113, v136
	v_lshlrev_b32_e32 v184, 5, v184
	v_and_b32_e32 v184, 0x1fea0, v184
	v_or_b32_e32 v184, v184, v131
	v_lshlrev_b32_e32 v184, 3, v184
	global_load_dwordx2 v[170:171], v184, s[4:5]
	v_or_b32_e32 v184, 114, v136
	v_lshlrev_b32_e32 v184, 5, v184
	v_and_b32_e32 v184, 0x1fec0, v184
	v_or_b32_e32 v184, v184, v131
	v_lshlrev_b32_e32 v184, 3, v184
	global_load_dwordx2 v[172:173], v184, s[4:5]
	v_or_b32_e32 v184, 115, v136
	v_lshlrev_b32_e32 v184, 5, v184
	v_and_b32_e32 v184, 0x1fee0, v184
	v_or_b32_e32 v184, v184, v131
	v_lshlrev_b32_e32 v184, 3, v184
	global_load_dwordx2 v[174:175], v184, s[4:5]
	v_or_b32_e32 v184, 120, v136
	v_lshlrev_b32_e32 v184, 5, v184
	v_and_b32_e32 v184, 0x1ff80, v184
	v_or_b32_e32 v184, v184, v131
	v_lshlrev_b32_e32 v184, 3, v184
	global_load_dwordx2 v[176:177], v184, s[4:5]
	v_or_b32_e32 v184, 121, v136
	v_lshlrev_b32_e32 v184, 5, v184
	v_and_b32_e32 v184, 0x1ffa0, v184
	v_or_b32_e32 v184, v184, v131
	v_lshlrev_b32_e32 v184, 3, v184
	global_load_dwordx2 v[178:179], v184, s[4:5]
	v_or_b32_e32 v184, 122, v136
	v_lshlrev_b32_e32 v184, 5, v184
	v_and_b32_e32 v184, 0x1ffc0, v184
	v_or_b32_e32 v184, v184, v131
	v_lshlrev_b32_e32 v184, 3, v184
	global_load_dwordx2 v[180:181], v184, s[4:5]
	v_or_b32_e32 v184, 123, v136
	v_lshlrev_b32_e32 v184, 5, v184
	v_and_b32_e32 v184, 0x1ffe0, v184
	v_or_b32_e32 v184, v184, v131
	v_lshlrev_b32_e32 v184, 3, v184
	global_load_dwordx2 v[182:183], v184, s[4:5]
	v_add_f32_e32 v142, v2, v130
	v_add_f32_e32 v137, v18, v132
	s_waitcnt vmcnt(15)
; DI u16 f2bf(float x) { return (u16)(pack2(x, 0.f) & 0xffffu); }
; DI int crow(int i, int h) { return (i & 3) + 8 * (i >> 2) + 4 * h; }
; DI void phase_m1(const Params& p, int l, int grp, char* smem) {
;     ...
;       for (int ms = 0; ms < 4; ++ms)
; #pragma unroll
;         for (int i = 0; i < 16; ++i) {
;           const int row = mt * 256 + wm * 128 + ms * 32 + crow(i, lh);
;           const int pos = row & 4095;
;           const float2 cs = t64[pos * 32 + lr];
;           const float x1 = acc[ms][0][i] + bias0, x2 = acc[ms][1][i] + bias1;
;           z[(size_t)row * ZW + cb0 + lr] = f2bf(x1 * cs.x - x2 * cs.y);
;           z[(size_t)row * ZW + cb0 + 32 + lr] = f2bf(x1 * cs.y + x2 * cs.x);
;         }
	v_mul_f32_e32 v140, v142, v145
	v_fma_f32 v140, v137, v144, -v140
	v_cvt_pk_bf16_f32 v143, v140, s0
	v_mad_i64_i32 v[140:141], s[6:7], v0, s8, v[134:135]
	v_mul_f32_e32 v0, v137, v145
	v_fmac_f32_e32 v0, v142, v144
	v_cvt_pk_bf16_f32 v0, v0, s0
	global_store_short v[140:141], v0, off offset:64
	v_or_b32_e32 v0, 0x61, v136
	v_lshlrev_b32_e32 v137, 5, v0
	s_mov_b32 s6, 0x1fca0
	v_and_or_b32 v137, v137, s6, v131
	global_store_short v[140:141], v143, off
	v_lshlrev_b32_e32 v137, 3, v137
	v_add_f32_e32 v142, v3, v130
	v_add_f32_e32 v137, v19, v132
	s_waitcnt vmcnt(16)
	v_mul_f32_e32 v140, v142, v147
	v_fma_f32 v140, v137, v146, -v140
	v_cvt_pk_bf16_f32 v143, v140, s0
	v_mad_i64_i32 v[140:141], s[6:7], v0, s8, v[134:135]
	v_mul_f32_e32 v0, v137, v147
	v_fmac_f32_e32 v0, v142, v146
	v_cvt_pk_bf16_f32 v0, v0, s0
	global_store_short v[140:141], v0, off offset:64
	v_or_b32_e32 v0, 0x62, v136
	v_lshlrev_b32_e32 v137, 5, v0
	s_mov_b32 s6, 0x1fcc0
	v_and_or_b32 v137, v137, s6, v131
	global_store_short v[140:141], v143, off
	v_lshlrev_b32_e32 v137, 3, v137
	v_add_f32_e32 v142, v4, v130
	v_add_f32_e32 v137, v20, v132
	s_waitcnt vmcnt(17)
	v_mul_f32_e32 v140, v142, v149
	v_fma_f32 v140, v137, v148, -v140
	v_cvt_pk_bf16_f32 v143, v140, s0
	v_mad_i64_i32 v[140:141], s[6:7], v0, s8, v[134:135]
	v_mul_f32_e32 v0, v137, v149
	v_fmac_f32_e32 v0, v142, v148
	v_cvt_pk_bf16_f32 v0, v0, s0
	global_store_short v[140:141], v0, off offset:64
	v_or_b32_e32 v0, 0x63, v136
	v_lshlrev_b32_e32 v137, 5, v0
	s_mov_b32 s6, 0x1fce0
	v_and_or_b32 v137, v137, s6, v131
	global_store_short v[140:141], v143, off
	v_lshlrev_b32_e32 v137, 3, v137
	v_add_f32_e32 v142, v5, v130
	v_add_f32_e32 v137, v21, v132
	s_waitcnt vmcnt(18)
	v_mul_f32_e32 v140, v142, v151
	v_fma_f32 v140, v137, v150, -v140
	v_cvt_pk_bf16_f32 v143, v140, s0
	v_mad_i64_i32 v[140:141], s[6:7], v0, s8, v[134:135]
	v_mul_f32_e32 v0, v137, v151
	v_fmac_f32_e32 v0, v142, v150
	v_cvt_pk_bf16_f32 v0, v0, s0
	global_store_short v[140:141], v0, off offset:64
	v_or_b32_e32 v0, 0x68, v136
	v_lshlrev_b32_e32 v137, 5, v0
	s_mov_b32 s6, 0x1fd80
	v_and_or_b32 v137, v137, s6, v131
	global_store_short v[140:141], v143, off
	v_lshlrev_b32_e32 v137, 3, v137
	v_add_f32_e32 v142, v6, v130
	v_add_f32_e32 v137, v22, v132
	s_waitcnt vmcnt(19)
	v_mul_f32_e32 v140, v142, v153
	v_fma_f32 v140, v137, v152, -v140
	v_cvt_pk_bf16_f32 v143, v140, s0
	v_mad_i64_i32 v[140:141], s[6:7], v0, s8, v[134:135]
	v_mul_f32_e32 v0, v137, v153
	v_fmac_f32_e32 v0, v142, v152
	v_cvt_pk_bf16_f32 v0, v0, s0
	global_store_short v[140:141], v0, off offset:64
	v_or_b32_e32 v0, 0x69, v136
	v_lshlrev_b32_e32 v137, 5, v0
	s_mov_b32 s6, 0x1fda0
	v_and_or_b32 v137, v137, s6, v131
	global_store_short v[140:141], v143, off
	v_lshlrev_b32_e32 v137, 3, v137
	v_add_f32_e32 v142, v7, v130
	v_add_f32_e32 v137, v23, v132
	s_waitcnt vmcnt(20)
	v_mul_f32_e32 v140, v142, v155
	v_fma_f32 v140, v137, v154, -v140
	v_cvt_pk_bf16_f32 v143, v140, s0
	v_mad_i64_i32 v[140:141], s[6:7], v0, s8, v[134:135]
	v_mul_f32_e32 v0, v137, v155
	v_fmac_f32_e32 v0, v142, v154
	v_cvt_pk_bf16_f32 v0, v0, s0
	global_store_short v[140:141], v0, off offset:64
	v_or_b32_e32 v0, 0x6a, v136
	v_lshlrev_b32_e32 v137, 5, v0
	s_mov_b32 s6, 0x1fdc0
	v_and_or_b32 v137, v137, s6, v131
	global_store_short v[140:141], v143, off
	v_lshlrev_b32_e32 v137, 3, v137
	v_add_f32_e32 v142, v8, v130
	v_add_f32_e32 v137, v24, v132
	s_waitcnt vmcnt(21)
	v_mul_f32_e32 v140, v142, v157
	v_fma_f32 v140, v137, v156, -v140
	v_cvt_pk_bf16_f32 v143, v140, s0
	v_mad_i64_i32 v[140:141], s[6:7], v0, s8, v[134:135]
	v_mul_f32_e32 v0, v137, v157
	v_fmac_f32_e32 v0, v142, v156
	v_cvt_pk_bf16_f32 v0, v0, s0
	global_store_short v[140:141], v0, off offset:64
	v_or_b32_e32 v0, 0x6b, v136
	v_lshlrev_b32_e32 v137, 5, v0
	s_mov_b32 s6, 0x1fde0
	v_and_or_b32 v137, v137, s6, v131
	global_store_short v[140:141], v143, off
	v_lshlrev_b32_e32 v137, 3, v137
	v_add_f32_e32 v142, v9, v130
	v_add_f32_e32 v137, v25, v132
	s_waitcnt vmcnt(22)
	v_mul_f32_e32 v140, v142, v159
	v_fma_f32 v140, v137, v158, -v140
	v_cvt_pk_bf16_f32 v143, v140, s0
	v_mad_i64_i32 v[140:141], s[6:7], v0, s8, v[134:135]
	v_mul_f32_e32 v0, v137, v159
	v_fmac_f32_e32 v0, v142, v158
	v_cvt_pk_bf16_f32 v0, v0, s0
	global_store_short v[140:141], v0, off offset:64
	v_or_b32_e32 v0, 0x70, v136
	v_lshlrev_b32_e32 v137, 5, v0
	s_mov_b32 s6, 0x1fe80
	v_and_or_b32 v137, v137, s6, v131
	global_store_short v[140:141], v143, off
	v_lshlrev_b32_e32 v137, 3, v137
	v_add_f32_e32 v142, v10, v130
	v_add_f32_e32 v137, v26, v132
	s_waitcnt vmcnt(23)
; DI u16 f2bf(float x) { return (u16)(pack2(x, 0.f) & 0xffffu); }
; DI int crow(int i, int h) { return (i & 3) + 8 * (i >> 2) + 4 * h; }
; DI void phase_m1(const Params& p, int l, int grp, char* smem) {
;     ...
;       for (int ms = 0; ms < 4; ++ms)
; #pragma unroll
;         for (int i = 0; i < 16; ++i) {
;           const int row = mt * 256 + wm * 128 + ms * 32 + crow(i, lh);
;           const int pos = row & 4095;
;           const float2 cs = t64[pos * 32 + lr];
;           const float x1 = acc[ms][0][i] + bias0, x2 = acc[ms][1][i] + bias1;
;           z[(size_t)row * ZW + cb0 + lr] = f2bf(x1 * cs.x - x2 * cs.y);
;           z[(size_t)row * ZW + cb0 + 32 + lr] = f2bf(x1 * cs.y + x2 * cs.x);
;         }
	v_mul_f32_e32 v140, v142, v161
	v_fma_f32 v140, v137, v160, -v140
	v_cvt_pk_bf16_f32 v143, v140, s0
	v_mad_i64_i32 v[140:141], s[6:7], v0, s8, v[134:135]
	v_mul_f32_e32 v0, v137, v161
	v_fmac_f32_e32 v0, v142, v160
	v_cvt_pk_bf16_f32 v0, v0, s0
	global_store_short v[140:141], v0, off offset:64
	v_or_b32_e32 v0, 0x71, v136
	v_lshlrev_b32_e32 v137, 5, v0
	s_mov_b32 s6, 0x1fea0
	v_and_or_b32 v137, v137, s6, v131
	global_store_short v[140:141], v143, off
	v_lshlrev_b32_e32 v137, 3, v137
	v_add_f32_e32 v142, v11, v130
	v_add_f32_e32 v137, v27, v132
	s_waitcnt vmcnt(24)
	v_mul_f32_e32 v140, v142, v171
	v_fma_f32 v140, v137, v170, -v140
	v_cvt_pk_bf16_f32 v143, v140, s0
	v_mad_i64_i32 v[140:141], s[6:7], v0, s8, v[134:135]
	v_mul_f32_e32 v0, v137, v171
	v_fmac_f32_e32 v0, v142, v170
	v_cvt_pk_bf16_f32 v0, v0, s0
	global_store_short v[140:141], v0, off offset:64
	v_or_b32_e32 v0, 0x72, v136
	v_lshlrev_b32_e32 v137, 5, v0
	s_mov_b32 s6, 0x1fec0
	v_and_or_b32 v137, v137, s6, v131
	global_store_short v[140:141], v143, off
	v_lshlrev_b32_e32 v137, 3, v137
	v_add_f32_e32 v142, v12, v130
	v_add_f32_e32 v137, v28, v132
	s_waitcnt vmcnt(25)
	v_mul_f32_e32 v140, v142, v173
	v_fma_f32 v140, v137, v172, -v140
	v_cvt_pk_bf16_f32 v143, v140, s0
	v_mad_i64_i32 v[140:141], s[6:7], v0, s8, v[134:135]
	v_mul_f32_e32 v0, v137, v173
	v_fmac_f32_e32 v0, v142, v172
	v_cvt_pk_bf16_f32 v0, v0, s0
	global_store_short v[140:141], v0, off offset:64
	v_or_b32_e32 v0, 0x73, v136
	v_lshlrev_b32_e32 v137, 5, v0
	s_mov_b32 s6, 0x1fee0
	v_and_or_b32 v137, v137, s6, v131
	global_store_short v[140:141], v143, off
	v_lshlrev_b32_e32 v137, 3, v137
	v_add_f32_e32 v142, v13, v130
	v_add_f32_e32 v137, v29, v132
	s_waitcnt vmcnt(26)
	v_mul_f32_e32 v140, v142, v175
	v_fma_f32 v140, v137, v174, -v140
	v_cvt_pk_bf16_f32 v143, v140, s0
	v_mad_i64_i32 v[140:141], s[6:7], v0, s8, v[134:135]
	v_mul_f32_e32 v0, v137, v175
	v_fmac_f32_e32 v0, v142, v174
	v_cvt_pk_bf16_f32 v0, v0, s0
	global_store_short v[140:141], v0, off offset:64
	v_or_b32_e32 v0, 0x78, v136
	v_lshlrev_b32_e32 v137, 5, v0
	s_mov_b32 s6, 0x1ff80
	v_and_or_b32 v137, v137, s6, v131
	global_store_short v[140:141], v143, off
	v_lshlrev_b32_e32 v137, 3, v137
	v_add_f32_e32 v142, v14, v130
	v_add_f32_e32 v137, v30, v132
	s_waitcnt vmcnt(27)
	v_mul_f32_e32 v140, v142, v177
	v_fma_f32 v140, v137, v176, -v140
	v_cvt_pk_bf16_f32 v143, v140, s0
	v_mad_i64_i32 v[140:141], s[6:7], v0, s8, v[134:135]
	v_mul_f32_e32 v0, v137, v177
	v_fmac_f32_e32 v0, v142, v176
	v_cvt_pk_bf16_f32 v0, v0, s0
	global_store_short v[140:141], v0, off offset:64
	v_or_b32_e32 v0, 0x79, v136
	v_lshlrev_b32_e32 v137, 5, v0
	s_mov_b32 s6, 0x1ffa0
	v_and_or_b32 v137, v137, s6, v131
	global_store_short v[140:141], v143, off
	v_lshlrev_b32_e32 v137, 3, v137
	v_add_f32_e32 v142, v15, v130
	v_add_f32_e32 v137, v31, v132
	s_waitcnt vmcnt(28)
	v_mul_f32_e32 v140, v142, v179
	v_fma_f32 v140, v137, v178, -v140
	v_cvt_pk_bf16_f32 v143, v140, s0
	v_mad_i64_i32 v[140:141], s[6:7], v0, s8, v[134:135]
	v_mul_f32_e32 v0, v137, v179
	v_fmac_f32_e32 v0, v142, v178
	v_cvt_pk_bf16_f32 v0, v0, s0
	global_store_short v[140:141], v0, off offset:64
	v_or_b32_e32 v0, 0x7a, v136
	v_lshlrev_b32_e32 v137, 5, v0
	s_mov_b32 s6, 0x1ffc0
	v_and_or_b32 v137, v137, s6, v131
	global_store_short v[140:141], v143, off
	v_lshlrev_b32_e32 v137, 3, v137
	v_add_f32_e32 v142, v16, v130
	v_add_f32_e32 v137, v32, v132
	s_waitcnt vmcnt(29)
	v_mul_f32_e32 v140, v142, v181
	v_fma_f32 v140, v137, v180, -v140
	v_cvt_pk_bf16_f32 v143, v140, s0
	v_mad_i64_i32 v[140:141], s[6:7], v0, s8, v[134:135]
	v_mul_f32_e32 v0, v137, v181
	v_fmac_f32_e32 v0, v142, v180
	v_cvt_pk_bf16_f32 v0, v0, s0
	global_store_short v[140:141], v0, off offset:64
	v_or_b32_e32 v0, 0x7b, v136
	v_lshlrev_b32_e32 v136, 5, v0
	s_mov_b32 s6, 0x1ffe0
	v_and_or_b32 v136, v136, s6, v131
	global_store_short v[140:141], v143, off
	v_lshlrev_b32_e32 v136, 3, v136
	v_add_f32_e32 v138, v33, v132
	v_add_f32_e32 v139, v17, v130
	v_mad_i64_i32 v[134:135], s[6:7], v0, s8, v[134:135]
	s_waitcnt vmcnt(30)
	v_mul_f32_e32 v140, v139, v183
	v_mul_f32_e32 v0, v138, v183
	v_fma_f32 v140, v138, v182, -v140
	v_fmac_f32_e32 v0, v139, v182
	v_cvt_pk_bf16_f32 v140, v140, s0
	v_cvt_pk_bf16_f32 v0, v0, s0
	global_store_short v[134:135], v140, off
	global_store_short v[134:135], v0, off offset:64
